# v20 + P2c correction-item y stores write-through (sc0 sc1): less for the P2c->P3 barrier write-back to flush
# speedup vs baseline: 1.0050x; 1.0050x over previous
.LBB0_1005:
	s_or_b64 exec, exec, s[4:5]
	v_lshl_add_u64 v[48:49], s[26:27], 2, v[116:117]
	s_waitcnt lgkmcnt(0)
	s_barrier
	ds_read2st64_b32 v[52:53], v111 offset1:1
	ds_read2st64_b32 v[54:55], v111 offset0:2 offset1:3
	s_ashr_i32 s21, s20, 31
	s_lshl_b64 s[4:5], s[20:21], 22
	v_ashrrev_i32_e32 v81, 31, v80
	v_ashrrev_i32_e32 v83, 31, v82
	s_add_u32 s4, s0, s4
	v_lshlrev_b64 v[56:57], 11, v[80:81]
	v_lshlrev_b64 v[58:59], 11, v[82:83]
	s_addc_u32 s5, s1, s5
	s_waitcnt lgkmcnt(0)
	v_mov_b32_e32 v60, v54
	v_mov_b32_e32 v61, v52
	v_mov_b32_e32 v52, v55
	v_lshl_add_u64 v[56:57], s[4:5], 0, v[56:57]
	v_lshl_add_u64 v[58:59], s[4:5], 0, v[58:59]
	v_pk_add_f32 v[52:53], v[60:61], v[52:53]
	s_brev_b32 s4, 60
	v_pk_fma_f32 v[52:53], v[52:53], s[4:5], v[158:159] op_sel_hi:[1,0,0]
	v_lshl_add_u64 v[54:55], v[58:59], 0, s[28:29]
	v_mul_f32_e32 v58, 0x4b800000, v53
	v_mul_f32_e32 v59, 0x4b800000, v52
	v_cmp_gt_f32_e32 vcc, s75, v53
	v_cmp_gt_f32_e64 s[4:5], s75, v52
	v_lshl_add_u64 v[56:57], v[56:57], 0, s[28:29]
	v_cndmask_b32_e32 v53, v53, v58, vcc
	v_cndmask_b32_e64 v52, v52, v59, s[4:5]
	v_rsq_f32_e32 v58, v53
	v_rsq_f32_e32 v59, v52
	v_lshl_add_u64 v[52:53], v[56:57], 0, v[2:3]
	v_lshl_add_u64 v[54:55], v[54:55], 0, v[2:3]
	v_mul_f32_e32 v2, 0x45800000, v58
	v_mul_f32_e32 v56, 0x45800000, v59
	v_cndmask_b32_e32 v2, v58, v2, vcc
	v_cndmask_b32_e64 v56, v59, v56, s[4:5]
	v_pk_mul_f32 v[32:33], v[32:33], v[2:3] op_sel_hi:[1,0]
	v_pk_mul_f32 v[34:35], v[34:35], v[2:3] op_sel_hi:[1,0]
	v_pk_mul_f32 v[4:5], v[4:5], v[56:57] op_sel_hi:[1,0]
	v_pk_mul_f32 v[6:7], v[6:7], v[56:57] op_sel_hi:[1,0]
	v_pk_mul_f32 v[28:29], v[28:29], v[2:3] op_sel_hi:[1,0]
	v_pk_mul_f32 v[30:31], v[30:31], v[2:3] op_sel_hi:[1,0]
	v_pk_mul_f32 v[24:25], v[24:25], v[2:3] op_sel_hi:[1,0]
	v_pk_mul_f32 v[26:27], v[26:27], v[2:3] op_sel_hi:[1,0]
	v_pk_mul_f32 v[20:21], v[20:21], v[2:3] op_sel_hi:[1,0]
	v_pk_mul_f32 v[22:23], v[22:23], v[2:3] op_sel_hi:[1,0]
	v_pk_mul_f32 v[16:17], v[16:17], v[56:57] op_sel_hi:[1,0]
	v_pk_mul_f32 v[18:19], v[18:19], v[56:57] op_sel_hi:[1,0]
	v_pk_mul_f32 v[12:13], v[12:13], v[56:57] op_sel_hi:[1,0]
	v_pk_mul_f32 v[14:15], v[14:15], v[56:57] op_sel_hi:[1,0]
	s_mov_b64 s[4:5], 0
	s_waitcnt vmcnt(3)
	v_pk_mul_f32 v[32:33], v[172:173], v[32:33]
	v_pk_mul_f32 v[34:35], v[174:175], v[34:35]
	s_waitcnt vmcnt(1)
	v_pk_mul_f32 v[4:5], v[180:181], v[4:5]
	v_pk_mul_f32 v[6:7], v[182:183], v[6:7]
	v_pk_mul_f32 v[28:29], v[176:177], v[28:29]
	v_pk_mul_f32 v[30:31], v[178:179], v[30:31]
	v_pk_mul_f32 v[24:25], v[180:181], v[24:25]
	v_pk_mul_f32 v[26:27], v[182:183], v[26:27]
	s_waitcnt vmcnt(0)
	v_pk_mul_f32 v[20:21], v[184:185], v[20:21]
	v_pk_mul_f32 v[22:23], v[186:187], v[22:23]
	v_pk_mul_f32 v[16:17], v[172:173], v[16:17]
	v_pk_mul_f32 v[18:19], v[174:175], v[18:19]
	v_pk_mul_f32 v[12:13], v[176:177], v[12:13]
	v_pk_mul_f32 v[14:15], v[178:179], v[14:15]
	v_cvt_pk_bf16_f32 v32, v32, v33
	v_cvt_pk_bf16_f32 v33, v34, v35
	v_cvt_pk_bf16_f32 v4, v4, v5
	v_cvt_pk_bf16_f32 v5, v6, v7
	v_cvt_pk_bf16_f32 v28, v28, v29
	v_cvt_pk_bf16_f32 v29, v30, v31
	v_cvt_pk_bf16_f32 v24, v24, v25
	v_cvt_pk_bf16_f32 v25, v26, v27
	v_cvt_pk_bf16_f32 v20, v20, v21
	v_cvt_pk_bf16_f32 v21, v22, v23
	v_cvt_pk_bf16_f32 v16, v16, v17
	v_cvt_pk_bf16_f32 v17, v18, v19
	v_cvt_pk_bf16_f32 v12, v12, v13
	v_cvt_pk_bf16_f32 v13, v14, v15
	global_store_dwordx2 v[52:53], v[32:33], off offset:1024 sc0 sc1
	global_store_dwordx2 v[52:53], v[28:29], off offset:1056 sc0 sc1
	global_store_dwordx2 v[52:53], v[24:25], off offset:1088 sc0 sc1
	global_store_dwordx2 v[52:53], v[20:21], off offset:1120 sc0 sc1
	global_store_dwordx2 v[54:55], v[16:17], off offset:1024 sc0 sc1
	global_store_dwordx2 v[54:55], v[12:13], off offset:1056 sc0 sc1
	global_store_dwordx2 v[54:55], v[4:5], off offset:1088 sc0 sc1
	v_pk_mul_f32 v[4:5], v[8:9], v[56:57] op_sel_hi:[1,0]
	v_pk_mul_f32 v[6:7], v[10:11], v[56:57] op_sel_hi:[1,0]
	v_pk_mul_f32 v[4:5], v[184:185], v[4:5]
	v_pk_mul_f32 v[6:7], v[186:187], v[6:7]
	v_cvt_pk_bf16_f32 v4, v4, v5
	v_cvt_pk_bf16_f32 v5, v6, v7
	global_store_dwordx2 v[54:55], v[4:5], off offset:1120 sc0 sc1
	s_barrier

.LBB0_1009:
	s_ashr_i32 s21, s20, 31
	s_mul_i32 s7, s20, 0x1100000
	s_mul_hi_i32 s6, s20, 0x1100000
	s_add_u32 s26, s38, s7
	s_addc_u32 s27, s39, s6
	s_lshl_b64 s[6:7], s[20:21], 22
	s_add_u32 s6, s0, s6
	s_addc_u32 s7, s1, s7
	s_ashr_i32 s25, s24, 31
	s_lshl_b64 s[28:29], s[24:25], 13
	s_add_u32 s4, s40, s4
	s_addc_u32 s5, s41, s5
	s_mul_i32 s25, s22, 0x4100
	s_mul_hi_i32 s21, s22, 0x4100
	s_add_u32 s4, s4, s25
	s_addc_u32 s5, s5, s21
	v_lshlrev_b32_e32 v2, 2, v0
	v_lshl_add_u64 v[4:5], s[4:5], 0, v[2:3]
	v_add_co_u32_e32 v6, vcc, s65, v4
	v_lshlrev_b32_e32 v2, 1, v110
	s_nop 0
	v_addc_co_u32_e32 v7, vcc, 0, v5, vcc
	global_load_dword v168, v[6:7], off
	v_lshlrev_b32_e32 v6, 1, v106
	v_mov_b32_e32 v7, v3
	v_lshl_add_u64 v[8:9], s[4:5], 0, v[2:3]
	v_lshl_add_u64 v[6:7], v[8:9], 0, v[6:7]
	v_add_co_u32_e32 v12, vcc, s63, v6
	s_mov_b64 s[4:5], 0x2000
	s_nop 0
	v_addc_co_u32_e32 v13, vcc, 0, v7, vcc
	v_lshlrev_b32_e32 v2, 1, v112
	v_add_co_u32_e32 v4, vcc, s58, v4
	v_lshl_add_u64 v[10:11], v[6:7], 0, s[4:5]
	global_load_dwordx4 v[24:27], v[12:13], off
	global_load_dwordx4 v[20:23], v[10:11], off offset:64
	v_lshl_add_u64 v[12:13], v[8:9], 0, v[2:3]
	v_addc_co_u32_e32 v5, vcc, 0, v5, vcc
	s_mov_b64 s[4:5], 0x6100
	global_load_dwordx2 v[36:37], v[12:13], off
	global_load_dwordx2 v[48:49], v[12:13], off offset:32
	global_load_dwordx2 v[68:69], v[12:13], off offset:64
	global_load_dwordx2 v[58:59], v[12:13], off offset:96
	global_load_dword v2, v[4:5], off offset:256
	v_lshl_add_u64 v[4:5], v[6:7], 0, s[4:5]
	v_add_co_u32_e32 v6, vcc, s57, v6
	s_mov_b64 s[4:5], 0x4100
	s_nop 0
	v_addc_co_u32_e32 v7, vcc, 0, v7, vcc
	v_lshl_add_u64 v[14:15], v[12:13], 0, s[4:5]
	v_add_co_u32_e32 v12, vcc, s65, v12
	global_load_dwordx4 v[8:11], v[6:7], off offset:256
	s_nop 0
	global_load_dwordx4 v[4:7], v[4:5], off offset:64
	v_addc_co_u32_e32 v13, vcc, 0, v13, vcc
	global_load_dwordx2 v[184:185], v[12:13], off offset:256
	global_load_dwordx2 v[182:183], v[14:15], off offset:32
	global_load_dwordx2 v[180:181], v[14:15], off offset:64
	global_load_dwordx2 v[178:179], v[14:15], off offset:96
	v_lshl_add_u64 v[12:13], v[118:119], 0, s[28:29]
	s_mov_b64 s[4:5], 0x80000
	v_lshl_add_u64 v[14:15], v[12:13], 0, s[4:5]
	s_mov_b32 s4, 0x81000
	v_add_co_u32_e32 v12, vcc, s4, v12
	s_lshl_b32 s4, s55, 6
	s_nop 0
	v_addc_co_u32_e32 v13, vcc, 0, v13, vcc
	global_load_dwordx4 v[64:67], v[12:13], off offset:-4096
	global_load_dwordx4 v[60:63], v[14:15], off offset:64
	global_load_dwordx4 v[44:47], v[14:15], off offset:2048
	global_load_dwordx4 v[40:43], v[14:15], off offset:2112
	global_load_dwordx4 v[32:35], v[12:13], off
	global_load_dwordx4 v[28:31], v[12:13], off offset:64
	global_load_dwordx4 v[16:19], v[12:13], off offset:2048
	s_nop 0
	global_load_dwordx4 v[12:15], v[12:13], off offset:2112
	v_or_b32_e32 v78, s4, v112
	s_lshl_b32 s5, s54, 6
	v_or_b32_e32 v76, s5, v0
	v_mov_b64_e32 v[38:39], s[26:27]
	v_add_u32_e32 v74, 16, v78
	v_or_b32_e32 v86, 32, v78
	v_ashrrev_i32_e32 v79, 31, v78
	v_mad_i64_i32 v[50:51], s[26:27], v76, s64, v[38:39]
	s_mov_b64 s[28:29], 0x1600
	v_add_u32_e32 v52, -1, v76
	v_ashrrev_i32_e32 v75, 31, v74
	v_ashrrev_i32_e32 v87, 31, v86
	v_lshl_add_u64 v[70:71], v[50:51], 0, s[72:73]
	v_lshl_add_u64 v[50:51], v[50:51], 0, s[28:29]
	v_mad_i64_i32 v[52:53], s[26:27], v52, s64, v[38:39]
	v_lshlrev_b64 v[148:149], 1, v[78:79]
	v_lshlrev_b64 v[74:75], 1, v[74:75]
	v_lshlrev_b64 v[86:87], 1, v[86:87]
	v_lshl_add_u64 v[72:73], v[52:53], 0, s[28:29]
	v_lshl_add_u64 v[54:55], v[50:51], 0, v[148:149]
	v_lshl_add_u64 v[80:81], v[70:71], 0, v[74:75]
	v_lshl_add_u64 v[88:89], v[70:71], 0, v[86:87]
	global_load_dwordx2 v[54:55], v[54:55], off
	v_lshl_add_u64 v[84:85], v[72:73], 0, v[74:75]
	global_load_dwordx2 v[80:81], v[80:81], off
	v_lshl_add_u64 v[52:53], v[70:71], 0, v[148:149]
	global_load_dwordx2 v[90:91], v[88:89], off
	v_lshl_add_u64 v[88:89], v[50:51], 0, v[86:87]
	global_load_dwordx2 v[84:85], v[84:85], off
	v_lshl_add_u64 v[82:83], v[50:51], 0, v[74:75]
	global_load_dwordx2 v[92:93], v[88:89], off
	v_lshl_add_u64 v[88:89], v[72:73], 0, v[86:87]
	global_load_dwordx2 v[94:95], v[88:89], off
	v_add_u32_e32 v88, 48, v78
	v_ashrrev_i32_e32 v89, 31, v88
	v_lshlrev_b64 v[88:89], 1, v[88:89]
	v_lshl_add_u64 v[70:71], v[70:71], 0, v[88:89]
	v_lshl_add_u64 v[50:51], v[50:51], 0, v[88:89]
	global_load_dwordx2 v[52:53], v[52:53], off
	v_add_u32_e32 v176, s5, v1
	global_load_dwordx2 v[82:83], v[82:83], off
	v_lshl_add_u64 v[56:57], v[72:73], 0, v[148:149]
	global_load_dwordx2 v[190:191], v[70:71], off
	global_load_dwordx2 v[192:193], v[50:51], off
	v_lshl_add_u64 v[50:51], v[72:73], 0, v[88:89]
	global_load_dwordx2 v[194:195], v[50:51], off
	v_mad_i64_i32 v[50:51], s[26:27], v176, s64, v[38:39]
	v_lshl_add_u64 v[70:71], v[50:51], 0, s[72:73]
	v_add_u32_e32 v72, -1, v176
	v_lshl_add_u64 v[50:51], v[50:51], 0, s[28:29]
	v_mad_i64_i32 v[38:39], s[26:27], v72, s64, v[38:39]
	v_lshl_add_u64 v[72:73], v[70:71], 0, v[148:149]
	v_lshl_add_u64 v[38:39], v[38:39], 0, s[28:29]
	global_load_dwordx2 v[172:173], v[72:73], off
	v_lshl_add_u64 v[72:73], v[50:51], 0, v[148:149]
	global_load_dwordx2 v[170:171], v[72:73], off
	v_lshl_add_u64 v[72:73], v[38:39], 0, v[148:149]
	global_load_dwordx2 v[174:175], v[72:73], off
	v_lshl_add_u64 v[72:73], v[70:71], 0, v[74:75]
	global_load_dwordx2 v[150:151], v[72:73], off
	v_lshl_add_u64 v[72:73], v[50:51], 0, v[74:75]
	global_load_dwordx2 v[152:153], v[72:73], off
	v_lshl_add_u64 v[72:73], v[38:39], 0, v[74:75]
	global_load_dwordx2 v[154:155], v[72:73], off
	v_lshl_add_u64 v[72:73], v[70:71], 0, v[86:87]
	global_load_dwordx2 v[142:143], v[72:73], off
	v_lshl_add_u64 v[72:73], v[50:51], 0, v[86:87]
	global_load_dwordx2 v[144:145], v[72:73], off
	v_lshl_add_u64 v[72:73], v[38:39], 0, v[86:87]
	v_lshl_add_u64 v[70:71], v[70:71], 0, v[88:89]
	v_lshl_add_u64 v[50:51], v[50:51], 0, v[88:89]
	v_lshl_add_u64 v[38:39], v[38:39], 0, v[88:89]
	global_load_dwordx2 v[56:57], v[56:57], off
	s_waitcnt vmcnt(35)
	v_lshlrev_b32_e32 v74, 16, v59
	global_load_dwordx2 v[136:137], v[70:71], off
	global_load_dwordx2 v[138:139], v[50:51], off
	global_load_dwordx2 v[140:141], v[38:39], off
	v_and_b32_e32 v39, 64, v234
	v_xor_b32_e32 v38, 16, v234
	v_add_u32_e32 v39, 64, v39
	v_cmp_lt_i32_e32 vcc, v38, v39
	global_load_dwordx2 v[146:147], v[72:73], off
	v_lshlrev_b32_e32 v70, 16, v36
	v_cndmask_b32_e32 v38, v234, v38, vcc
	v_lshlrev_b32_e32 v131, 2, v38
	v_xor_b32_e32 v38, 32, v234
	v_cmp_lt_i32_e32 vcc, v38, v39
	v_and_b32_e32 v71, 0xffff0000, v36
	v_lshlrev_b32_e32 v72, 16, v37
	v_cndmask_b32_e32 v38, v234, v38, vcc
	v_and_b32_e32 v73, 0xffff0000, v37
	v_lshlrev_b32_e32 v129, 2, v38
	v_and_b32_e32 v75, 0xffff0000, v59
	s_waitcnt vmcnt(31)
	v_mfma_f32_16x16x32_bf16 v[36:39], v[64:67], v[24:27], v[70:73]
	s_ashr_i32 s5, s4, 31
	v_ashrrev_i32_e32 v77, 31, v76
	v_lshl_add_u64 v[102:103], s[4:5], 2, v[126:127]
	s_waitcnt vmcnt(30)
	v_mfma_f32_16x16x32_bf16 v[36:39], v[60:63], v[20:23], v[36:39]
	v_lshlrev_b32_e32 v72, 16, v49
	v_and_b32_e32 v73, 0xffff0000, v49
	v_ashrrev_i32_e32 v177, 31, v176
	s_waitcnt vmcnt(22)
	v_lshlrev_b32_e32 v100, 16, v80
	v_and_b32_e32 v101, 0xffff0000, v80
	s_nop 1
	v_mov_b32_e32 v50, v37
	v_mov_b32_e32 v51, v38
	v_mov_b32_e32 v70, v36
	v_mov_b32_e32 v71, v39
	v_pk_add_f32 v[50:51], v[50:51], v[70:71]
	v_lshlrev_b32_e32 v70, 16, v48
	v_add_f32_e32 v50, v50, v51
	v_and_b32_e32 v71, 0xffff0000, v48
	v_add_f32_e32 v86, 0, v50
	v_mul_f32_e32 v80, 0xbfb8aa3b, v100
	v_mfma_f32_16x16x32_bf16 v[48:51], v[44:47], v[24:27], v[70:73]
	v_exp_f32_e32 v80, v80
	s_waitcnt vmcnt(17)
	v_and_b32_e32 v59, 0xffff0000, v52
	v_lshlrev_b32_e32 v208, 16, v84
	v_mfma_f32_16x16x32_bf16 v[48:51], v[40:43], v[20:23], v[48:51]
	v_add_f32_e32 v80, 1.0, v80
	v_rcp_f32_e32 v212, v80
	v_mul_f32_e32 v80, 0xbfb8aa3b, v101
	v_exp_f32_e32 v80, v80
	s_waitcnt vmcnt(16)
	v_lshlrev_b32_e32 v196, 16, v82
	s_nop 1
	v_mov_b32_e32 v70, v49
	v_mov_b32_e32 v71, v50
	v_mov_b32_e32 v72, v48
	v_mov_b32_e32 v73, v51
	v_pk_add_f32 v[70:71], v[70:71], v[72:73]
	v_lshlrev_b32_e32 v72, 16, v69
	v_pk_add_f32 v[88:89], v[70:71], v[70:71] op_sel:[0,1] op_sel_hi:[1,0]
	v_lshlrev_b32_e32 v70, 16, v68
	v_and_b32_e32 v71, 0xffff0000, v68
	v_and_b32_e32 v73, 0xffff0000, v69
	v_add_f32_e32 v80, 1.0, v80
	v_rcp_f32_e32 v213, v80
	v_mfma_f32_16x16x32_bf16 v[68:71], v[32:35], v[24:27], v[70:73]
	v_and_b32_e32 v197, 0xffff0000, v82
	v_and_b32_e32 v209, 0xffff0000, v84
	v_lshlrev_b32_e32 v82, 16, v83
	v_lshlrev_b32_e32 v72, 16, v58
	v_and_b32_e32 v73, 0xffff0000, v58
	v_mfma_f32_16x16x32_bf16 v[68:71], v[28:31], v[20:23], v[68:71]
	v_and_b32_e32 v83, 0xffff0000, v83
	v_lshlrev_b32_e32 v84, 16, v85
	v_and_b32_e32 v85, 0xffff0000, v85
	v_mfma_f32_16x16x32_bf16 v[24:27], v[16:19], v[24:27], v[72:75]
	v_lshlrev_b32_e32 v80, 16, v81
	s_nop 2
	v_add_f32_e32 v96, v68, v69
	v_add_f32_e32 v98, v70, v71
	v_mfma_f32_16x16x32_bf16 v[72:75], v[12:15], v[20:23], v[24:27]
	v_and_b32_e32 v81, 0xffff0000, v81
	v_pk_add_f32 v[84:85], v[84:85], v[82:83] neg_lo:[0,1] neg_hi:[0,1]
	v_pk_mul_f32 v[212:213], v[212:213], v[100:101]
	v_mul_f32_e32 v100, 0xbfb8aa3b, v80
	v_exp_f32_e32 v100, v100
	s_nop 2
	v_mov_b32_e32 v87, v72
	v_mov_b32_e32 v89, v73
	v_mov_b32_e32 v97, v74
	v_mov_b32_e32 v99, v75
	v_pk_add_f32 v[20:21], v[86:87], v[88:89]
	v_pk_add_f32 v[22:23], v[96:97], v[98:99]
	v_lshlrev_b32_e32 v86, 16, v54
	v_pk_add_f32 v[20:21], v[20:21], v[22:23]
	v_and_b32_e32 v87, 0xffff0000, v54
	v_add_f32_e32 v20, v20, v21
	ds_bpermute_b32 v21, v131, v20
	s_waitcnt vmcnt(4)
	v_lshlrev_b32_e32 v88, 16, v56
	v_and_b32_e32 v89, 0xffff0000, v56
	v_lshlrev_b32_e32 v54, 16, v55
	v_and_b32_e32 v55, 0xffff0000, v55
	s_waitcnt lgkmcnt(0)
	v_add_f32_e32 v20, v20, v21
	ds_bpermute_b32 v21, v129, v20
	v_lshlrev_b32_e32 v56, 16, v57
	v_and_b32_e32 v57, 0xffff0000, v57
	v_pk_add_f32 v[56:57], v[56:57], v[54:55] neg_lo:[0,1] neg_hi:[0,1]
	v_pk_add_f32 v[88:89], v[88:89], v[86:87] neg_lo:[0,1] neg_hi:[0,1]
	s_waitcnt lgkmcnt(0)
	v_add_f32_e32 v58, v20, v21
	v_fmamk_f32 v189, v58, 0xbc800000, v37
	v_fmamk_f32 v188, v58, 0xbc800000, v36
	v_fmamk_f32 v39, v58, 0xbc800000, v39
	v_fmac_f32_e32 v38, 0xbc800000, v58
	v_pk_mul_f32 v[20:21], v[38:39], v[38:39]
	v_pk_mul_f32 v[22:23], v[188:189], v[188:189]
	v_fmamk_f32 v187, v58, 0xbc800000, v49
	v_pk_mov_b32 v[24:25], v[22:23], v[20:21] op_sel:[1,0]
	v_mov_b32_e32 v23, v21
	v_pk_add_f32 v[20:21], v[24:25], v[22:23]
	v_fmamk_f32 v186, v58, 0xbc800000, v48
	v_fmamk_f32 v51, v58, 0xbc800000, v51
	v_fmac_f32_e32 v50, 0xbc800000, v58
	v_pk_add_f32 v[20:21], v[20:21], v[20:21] op_sel_hi:[0,1]
	v_pk_mul_f32 v[22:23], v[50:51], v[50:51]
	v_pk_mul_f32 v[24:25], v[186:187], v[186:187]
	v_fmac_f32_e32 v68, 0xbc800000, v58
	v_pk_mov_b32 v[26:27], v[24:25], v[22:23] op_sel:[1,0]
	v_mov_b32_e32 v25, v23
	v_fmamk_f32 v48, v58, 0xbc800000, v70
	v_fmamk_f32 v69, v58, 0xbc800000, v69
	v_mul_f32_e32 v20, v68, v68
	v_pk_add_f32 v[22:23], v[26:27], v[24:25]
	v_fmamk_f32 v49, v58, 0xbc800000, v71
	v_pk_fma_f32 v[24:25], v[68:69], v[68:69], v[20:21] op_sel_hi:[1,1,0]
	v_mul_f32_e32 v20, v48, v48
	v_pk_add_f32 v[22:23], v[22:23], v[22:23] op_sel_hi:[0,1]
	v_pk_fma_f32 v[26:27], v[48:49], v[48:49], v[20:21] op_sel_hi:[1,1,0]
	v_fmamk_f32 v37, v58, 0xbc800000, v75
	v_fmamk_f32 v36, v58, 0xbc800000, v74
	v_fmamk_f32 v73, v58, 0xbc800000, v73
	v_fmac_f32_e32 v72, 0xbc800000, v58
	v_mul_f32_e32 v24, v72, v72
	v_mul_f32_e32 v26, v73, v73
	v_mul_f32_e32 v20, v36, v36
	v_mul_f32_e32 v22, v37, v37
	v_pk_add_f32 v[24:25], v[24:25], v[26:27]
	v_pk_add_f32 v[20:21], v[20:21], v[22:23]
	v_lshlrev_b32_e32 v58, 16, v52
	v_pk_add_f32 v[70:71], v[24:25], v[20:21]
	v_lshlrev_b64 v[20:21], 11, v[76:77]
	global_load_dwordx4 v[74:77], v[102:103], off offset:2048
	v_mul_f32_e32 v52, 0xbfb8aa3b, v58
	v_exp_f32_e32 v52, v52
	v_lshlrev_b64 v[24:25], 2, v[78:79]
	v_mov_b32_e32 v79, s5
	v_lshl_add_u64 v[98:99], s[6:7], 0, v[20:21]
	v_add_f32_e32 v52, 1.0, v52
	v_rcp_f32_e32 v96, v52
	v_mul_f32_e32 v52, 0xbfb8aa3b, v59
	v_exp_f32_e32 v52, v52
	v_lshl_add_u64 v[20:21], s[8:9], 0, v[24:25]
	v_lshl_add_u64 v[24:25], s[10:11], 0, v[24:25]
	global_load_dwordx4 v[20:23], v[20:21], off
	v_add_f32_e32 v52, 1.0, v52
	v_rcp_f32_e32 v97, v52
	v_lshlrev_b32_e32 v52, 16, v53
	v_and_b32_e32 v53, 0xffff0000, v53
	global_load_dwordx4 v[24:27], v[24:25], off
	v_pk_mul_f32 v[200:201], v[96:97], v[58:59]
	v_mul_f32_e32 v58, 0xbfb8aa3b, v52
	v_exp_f32_e32 v58, v58
	v_add_f32_e32 v100, 1.0, v100
	v_rcp_f32_e32 v100, v100
	v_pk_add_f32 v[208:209], v[208:209], v[196:197] neg_lo:[0,1] neg_hi:[0,1]
	v_add_f32_e32 v58, 1.0, v58
	v_rcp_f32_e32 v58, v58
	v_lshl_add_u64 v[204:205], v[98:99], 0, v[148:149]
	v_lshlrev_b32_e32 v220, 16, v90
	v_and_b32_e32 v221, 0xffff0000, v90
	v_mul_f32_e32 v90, 0xbfb8aa3b, v220
	v_exp_f32_e32 v90, v90
	v_lshlrev_b32_e32 v218, 16, v92
	v_and_b32_e32 v219, 0xffff0000, v92
	v_lshlrev_b32_e32 v222, 16, v94
	v_add_f32_e32 v90, 1.0, v90
	v_rcp_f32_e32 v224, v90
	v_mul_f32_e32 v90, 0xbfb8aa3b, v221
	v_exp_f32_e32 v90, v90
	v_and_b32_e32 v223, 0xffff0000, v94
	v_lshlrev_b32_e32 v92, 16, v93
	v_and_b32_e32 v93, 0xffff0000, v93
	v_add_f32_e32 v90, 1.0, v90
	v_lshlrev_b32_e32 v94, 16, v95
	v_and_b32_e32 v95, 0xffff0000, v95
	v_pk_add_f32 v[222:223], v[222:223], v[218:219] neg_lo:[0,1] neg_hi:[0,1]
	v_rcp_f32_e32 v225, v90
	v_lshlrev_b32_e32 v90, 16, v91
	v_and_b32_e32 v91, 0xffff0000, v91
	v_pk_add_f32 v[94:95], v[94:95], v[92:93] neg_lo:[0,1] neg_hi:[0,1]
	v_mul_f32_e32 v133, 0xbfb8aa3b, v90
	v_exp_f32_e32 v133, v133
	v_pk_mul_f32 v[220:221], v[224:225], v[220:221]
	v_lshlrev_b32_e32 v228, 16, v190
	v_and_b32_e32 v229, 0xffff0000, v190
	v_add_f32_e32 v133, 1.0, v133
	v_rcp_f32_e32 v224, v133
	v_mul_f32_e32 v133, 0xbfb8aa3b, v228
	v_exp_f32_e32 v133, v133
	v_lshlrev_b32_e32 v226, 16, v192
	v_and_b32_e32 v227, 0xffff0000, v192
	v_lshlrev_b32_e32 v242, 16, v194
	v_add_f32_e32 v133, 1.0, v133
	v_rcp_f32_e32 v244, v133
	v_mul_f32_e32 v133, 0xbfb8aa3b, v229
	v_exp_f32_e32 v133, v133
	v_and_b32_e32 v243, 0xffff0000, v194
	v_pk_add_f32 v[242:243], v[242:243], v[226:227] neg_lo:[0,1] neg_hi:[0,1]
	v_lshlrev_b32_e32 v190, 16, v193
	v_add_f32_e32 v133, 1.0, v133
	v_rcp_f32_e32 v245, v133
	v_lshlrev_b32_e32 v192, 16, v195
	v_pk_mul_f32 v[228:229], v[244:245], v[228:229]
	v_lshlrev_b32_e32 v244, 16, v185
	v_and_b32_e32 v245, 0xffff0000, v185
	s_waitcnt vmcnt(2)
	v_pk_fma_f32 v[202:203], v[56:57], v[76:77], v[54:55]
	v_mul_f32_e32 v54, 0xbfb8aa3b, v53
	v_exp_f32_e32 v54, v54
	v_lshlrev_b64 v[56:57], 2, v[78:79]
	v_lshl_add_u64 v[96:97], s[8:9], 0, v[56:57]
	v_lshl_add_u64 v[104:105], s[10:11], 0, v[56:57]
	v_add_f32_e32 v54, 1.0, v54
	v_rcp_f32_e32 v59, v54
	v_pk_fma_f32 v[198:199], v[88:89], v[74:75], v[86:87]
	v_pk_mul_f32 v[206:207], v[58:59], v[52:53]
	global_load_dwordx4 v[52:55], v[96:97], off offset:64
	global_load_dwordx4 v[56:59], v[104:105], off offset:64
	global_load_dwordx4 v[86:89], v[102:103], off offset:2112
	s_waitcnt vmcnt(0)
	v_pk_fma_f32 v[214:215], v[84:85], v[88:89], v[82:83]
	v_mul_f32_e32 v82, 0xbfb8aa3b, v81
	v_exp_f32_e32 v82, v82
	v_pk_fma_f32 v[210:211], v[208:209], v[86:87], v[196:197]
	v_lshlrev_b64 v[196:197], 1, v[78:79]
	v_lshl_add_u64 v[208:209], v[98:99], 0, v[196:197]
	v_add_f32_e32 v82, 1.0, v82
	v_rcp_f32_e32 v101, v82
	s_nop 0
	v_pk_mul_f32 v[216:217], v[100:101], v[80:81]
	global_load_dwordx4 v[78:81], v[96:97], off offset:128
	global_load_dwordx4 v[82:85], v[104:105], off offset:128
	global_load_dwordx4 v[98:101], v[102:103], off offset:2176
	s_waitcnt vmcnt(0)
	v_pk_fma_f32 v[218:219], v[222:223], v[98:99], v[218:219]
	v_pk_fma_f32 v[222:223], v[94:95], v[100:101], v[92:93]
	v_mul_f32_e32 v92, 0xbfb8aa3b, v91
	v_exp_f32_e32 v92, v92
	s_nop 0
	v_add_f32_e32 v92, 1.0, v92
	v_rcp_f32_e32 v225, v92
	s_nop 0
	v_pk_mul_f32 v[224:225], v[224:225], v[90:91]
	global_load_dwordx4 v[90:93], v[96:97], off offset:192
	s_nop 0
	global_load_dwordx4 v[94:97], v[104:105], off offset:192
	s_nop 0
	global_load_dwordx4 v[102:105], v[102:103], off offset:2240
	s_waitcnt vmcnt(0)
	v_pk_fma_f32 v[226:227], v[242:243], v[102:103], v[226:227]
	v_lshlrev_b32_e32 v242, 16, v191
	v_mul_f32_e32 v133, 0xbfb8aa3b, v242
	v_exp_f32_e32 v133, v133
	v_and_b32_e32 v243, 0xffff0000, v191
	v_and_b32_e32 v191, 0xffff0000, v193
	v_and_b32_e32 v193, 0xffff0000, v195
	v_add_f32_e32 v133, 1.0, v133
	v_rcp_f32_e32 v194, v133
	v_mul_f32_e32 v133, 0xbfb8aa3b, v243
	v_exp_f32_e32 v133, v133
	v_pk_add_f32 v[192:193], v[192:193], v[190:191] neg_lo:[0,1] neg_hi:[0,1]
	v_add_f32_e32 v133, 1.0, v133
	v_rcp_f32_e32 v195, v133
	v_pk_fma_f32 v[190:191], v[192:193], v[104:105], v[190:191]
	v_pk_mul_f32 v[192:193], v[194:195], v[242:243]
	v_lshlrev_b32_e32 v242, 16, v184
	v_and_b32_e32 v243, 0xffff0000, v184
	s_nop 1
	v_mfma_f32_16x16x32_bf16 v[64:67], v[64:67], v[8:11], v[242:245]
	v_mfma_f32_16x16x32_bf16 v[60:63], v[60:63], v[4:7], v[64:67]
	s_nop 7
	v_mov_b32_e32 v64, v61
	v_mov_b32_e32 v65, v62
	v_mov_b32_e32 v66, v60
	v_mov_b32_e32 v67, v63
	v_pk_add_f32 v[64:65], v[64:65], v[66:67]
	v_lshlrev_b32_e32 v66, 16, v183
	v_add_f32_e32 v64, v64, v65
	v_add_f32_e32 v184, 0, v64
	v_lshlrev_b32_e32 v64, 16, v182
	v_and_b32_e32 v65, 0xffff0000, v182
	v_and_b32_e32 v67, 0xffff0000, v183
	s_nop 1
	v_mfma_f32_16x16x32_bf16 v[44:47], v[44:47], v[8:11], v[64:67]
	v_mfma_f32_16x16x32_bf16 v[40:43], v[40:43], v[4:7], v[44:47]
	s_nop 7
	v_mov_b32_e32 v44, v41
	v_mov_b32_e32 v45, v42
	v_mov_b32_e32 v46, v40
	v_mov_b32_e32 v47, v43
	v_pk_add_f32 v[44:45], v[44:45], v[46:47]
	v_lshlrev_b32_e32 v46, 16, v181
	v_pk_add_f32 v[64:65], v[44:45], v[44:45] op_sel:[0,1] op_sel_hi:[1,0]
	v_lshlrev_b32_e32 v44, 16, v180
	v_and_b32_e32 v45, 0xffff0000, v180
	v_and_b32_e32 v47, 0xffff0000, v181
	s_nop 1
	v_mfma_f32_16x16x32_bf16 v[32:35], v[32:35], v[8:11], v[44:47]
	v_mfma_f32_16x16x32_bf16 v[28:31], v[28:31], v[4:7], v[32:35]
	s_nop 6
	v_lshlrev_b32_e32 v32, 16, v178
	v_and_b32_e32 v33, 0xffff0000, v178
	v_lshlrev_b32_e32 v34, 16, v179
	v_and_b32_e32 v35, 0xffff0000, v179
	v_add_f32_e32 v44, v28, v29
	v_add_f32_e32 v46, v30, v31
	v_mfma_f32_16x16x32_bf16 v[8:11], v[16:19], v[8:11], v[32:35]
	v_mfma_f32_16x16x32_bf16 v[4:7], v[12:15], v[4:7], v[8:11]
	s_nop 1
	v_and_b32_e32 v33, 0xffff0000, v174
	s_nop 4
	v_mov_b32_e32 v185, v4
	v_mov_b32_e32 v65, v5
	v_mov_b32_e32 v45, v6
	v_mov_b32_e32 v47, v7
	v_pk_add_f32 v[8:9], v[184:185], v[64:65]
	v_pk_add_f32 v[10:11], v[44:45], v[46:47]
	s_nop 0
	v_pk_add_f32 v[8:9], v[8:9], v[10:11]
	s_nop 0
	v_add_f32_e32 v8, v8, v9
	ds_bpermute_b32 v9, v131, v8
	s_waitcnt lgkmcnt(0)
	v_add_f32_e32 v8, v8, v9
	ds_bpermute_b32 v9, v129, v8
	s_waitcnt lgkmcnt(0)
	v_add_f32_e32 v32, v8, v9
	v_fmamk_f32 v17, v32, 0xbc800000, v61
	v_fmamk_f32 v16, v32, 0xbc800000, v60
	v_fmamk_f32 v63, v32, 0xbc800000, v63
	v_fmac_f32_e32 v62, 0xbc800000, v32
	v_pk_mul_f32 v[8:9], v[62:63], v[62:63]
	v_pk_mul_f32 v[10:11], v[16:17], v[16:17]
	v_fmamk_f32 v43, v32, 0xbc800000, v43
	v_pk_mov_b32 v[12:13], v[10:11], v[8:9] op_sel:[1,0]
	v_mov_b32_e32 v11, v9
	v_pk_add_f32 v[8:9], v[12:13], v[10:11]
	v_fmamk_f32 v13, v32, 0xbc800000, v41
	v_fmamk_f32 v12, v32, 0xbc800000, v40
	v_fmac_f32_e32 v42, 0xbc800000, v32
	v_pk_mul_f32 v[10:11], v[42:43], v[42:43]
	v_pk_mul_f32 v[14:15], v[12:13], v[12:13]
	v_pk_add_f32 v[8:9], v[8:9], v[8:9] op_sel_hi:[0,1]
	v_pk_mov_b32 v[18:19], v[14:15], v[10:11] op_sel:[1,0]
	v_mov_b32_e32 v15, v11
	v_pk_add_f32 v[10:11], v[18:19], v[14:15]
	v_fmac_f32_e32 v28, 0xbc800000, v32
	v_pk_add_f32 v[14:15], v[10:11], v[10:11] op_sel_hi:[0,1]
	v_fmamk_f32 v10, v32, 0xbc800000, v30
	v_fmamk_f32 v29, v32, 0xbc800000, v29
	v_mul_f32_e32 v8, v28, v28
	v_fmamk_f32 v11, v32, 0xbc800000, v31
	v_pk_fma_f32 v[18:19], v[28:29], v[28:29], v[8:9] op_sel_hi:[1,1,0]
	v_mul_f32_e32 v8, v10, v10
	v_pk_fma_f32 v[30:31], v[10:11], v[10:11], v[8:9] op_sel_hi:[1,1,0]
	v_fmamk_f32 v7, v32, 0xbc800000, v7
	v_fmamk_f32 v6, v32, 0xbc800000, v6
	v_fmamk_f32 v5, v32, 0xbc800000, v5
	v_fmac_f32_e32 v4, 0xbc800000, v32
	v_mul_f32_e32 v18, v4, v4
	v_mul_f32_e32 v30, v5, v5
	v_mul_f32_e32 v8, v6, v6
	v_mul_f32_e32 v14, v7, v7
	v_pk_add_f32 v[18:19], v[18:19], v[30:31]
	v_pk_add_f32 v[8:9], v[8:9], v[14:15]
	v_mov_b32_e32 v15, v70
	v_pk_add_f32 v[8:9], v[18:19], v[8:9]
	v_lshlrev_b32_e32 v32, 16, v174
	v_mov_b32_e32 v14, v8
	v_mov_b32_e32 v70, v9
	v_pk_add_f32 v[8:9], v[14:15], v[70:71]
	ds_bpermute_b32 v15, v131, v9
	ds_bpermute_b32 v14, v131, v8
	s_waitcnt lgkmcnt(0)
	v_pk_add_f32 v[8:9], v[8:9], v[14:15]
	ds_bpermute_b32 v15, v129, v9
	ds_bpermute_b32 v14, v129, v8
	s_waitcnt lgkmcnt(0)
	v_pk_add_f32 v[8:9], v[8:9], v[14:15]
	s_nop 0
	v_pk_fma_f32 v[8:9], v[8:9], s[84:85], v[156:157] op_sel_hi:[1,0,0]
	s_nop 0
	v_mul_f32_e32 v14, 0x4b800000, v9
	v_cmp_gt_f32_e64 s[4:5], s75, v9
	v_cmp_gt_f32_e32 vcc, s75, v8
	s_nop 0
	v_cndmask_b32_e64 v9, v9, v14, s[4:5]
	v_rsq_f32_e32 v9, v9
	s_nop 0
	v_mul_f32_e32 v14, 0x45800000, v9
	v_cndmask_b32_e64 v14, v9, v14, s[4:5]
	v_pk_mul_f32 v[18:19], v[188:189], v[14:15] op_sel_hi:[1,0]
	v_pk_mul_f32 v[30:31], v[38:39], v[14:15] op_sel_hi:[1,0]
	v_pk_fma_f32 v[18:19], v[20:21], v[18:19], v[24:25]
	v_pk_fma_f32 v[30:31], v[22:23], v[30:31], v[26:27]
	v_pk_fma_f32 v[18:19], v[168:169], v[198:199], v[18:19] op_sel_hi:[0,1,1]
	v_pk_fma_f32 v[30:31], v[168:169], v[202:203], v[30:31] op_sel_hi:[0,1,1]
	v_pk_mul_f32 v[18:19], v[200:201], v[18:19]
	v_pk_mul_f32 v[30:31], v[206:207], v[30:31]
	v_cvt_pk_bf16_f32 v18, v18, v19
	v_cvt_pk_bf16_f32 v19, v30, v31
	global_store_dwordx2 v[204:205], v[18:19], off offset:1536 sc0 sc1
	v_pk_mul_f32 v[18:19], v[186:187], v[14:15] op_sel_hi:[1,0]
	v_pk_mul_f32 v[30:31], v[50:51], v[14:15] op_sel_hi:[1,0]
	v_pk_fma_f32 v[18:19], v[52:53], v[18:19], v[56:57]
	v_pk_fma_f32 v[30:31], v[54:55], v[30:31], v[58:59]
	v_pk_fma_f32 v[18:19], v[168:169], v[210:211], v[18:19] op_sel_hi:[0,1,1]
	v_pk_fma_f32 v[30:31], v[168:169], v[214:215], v[30:31] op_sel_hi:[0,1,1]
	v_pk_mul_f32 v[18:19], v[212:213], v[18:19]
	v_pk_mul_f32 v[30:31], v[216:217], v[30:31]
	v_cvt_pk_bf16_f32 v18, v18, v19
	v_cvt_pk_bf16_f32 v19, v30, v31
	global_store_dwordx2 v[208:209], v[18:19], off offset:1568 sc0 sc1
	v_pk_mul_f32 v[18:19], v[68:69], v[14:15] op_sel_hi:[1,0]
	v_pk_mul_f32 v[30:31], v[48:49], v[14:15] op_sel_hi:[1,0]
	v_pk_fma_f32 v[18:19], v[78:79], v[18:19], v[82:83]
	v_pk_fma_f32 v[30:31], v[80:81], v[30:31], v[84:85]
	v_pk_fma_f32 v[18:19], v[168:169], v[218:219], v[18:19] op_sel_hi:[0,1,1]
	v_pk_fma_f32 v[30:31], v[168:169], v[222:223], v[30:31] op_sel_hi:[0,1,1]
	v_pk_mul_f32 v[18:19], v[220:221], v[18:19]
	v_pk_mul_f32 v[30:31], v[224:225], v[30:31]
	v_cvt_pk_bf16_f32 v18, v18, v19
	v_cvt_pk_bf16_f32 v19, v30, v31
	v_mul_f32_e32 v9, 0x4b800000, v8
	global_store_dwordx2 v[208:209], v[18:19], off offset:1600 sc0 sc1
	v_pk_mul_f32 v[18:19], v[72:73], v[14:15] op_sel_hi:[1,0]
	v_pk_mul_f32 v[14:15], v[36:37], v[14:15] op_sel_hi:[1,0]
	v_cndmask_b32_e32 v8, v8, v9, vcc
	v_pk_fma_f32 v[18:19], v[90:91], v[18:19], v[94:95]
	v_pk_fma_f32 v[14:15], v[92:93], v[14:15], v[96:97]
	v_rsq_f32_e32 v8, v8
	v_pk_fma_f32 v[18:19], v[168:169], v[226:227], v[18:19] op_sel_hi:[0,1,1]
	v_pk_fma_f32 v[14:15], v[168:169], v[190:191], v[14:15] op_sel_hi:[0,1,1]
	v_pk_mul_f32 v[18:19], v[228:229], v[18:19]
	v_pk_mul_f32 v[14:15], v[192:193], v[14:15]
	v_cvt_pk_bf16_f32 v18, v18, v19
	v_cvt_pk_bf16_f32 v19, v14, v15
	global_store_dwordx2 v[208:209], v[18:19], off offset:1632 sc0 sc1
	v_mul_f32_e32 v9, 0x45800000, v8
	v_lshlrev_b32_e32 v18, 16, v172
	v_cndmask_b32_e32 v8, v8, v9, vcc
	v_mul_f32_e32 v9, 0xbfb8aa3b, v18
	v_exp_f32_e32 v9, v9
	v_and_b32_e32 v19, 0xffff0000, v172
	v_lshlrev_b32_e32 v30, 16, v170
	v_and_b32_e32 v31, 0xffff0000, v170
	v_add_f32_e32 v9, 1.0, v9
	v_rcp_f32_e32 v34, v9
	v_pk_mul_f32 v[16:17], v[16:17], v[8:9] op_sel_hi:[1,0]
	v_mul_f32_e32 v9, 0xbfb8aa3b, v19
	v_exp_f32_e32 v9, v9
	v_pk_add_f32 v[32:33], v[32:33], v[30:31] neg_lo:[0,1] neg_hi:[0,1]
	v_pk_fma_f32 v[16:17], v[20:21], v[16:17], v[24:25]
	v_pk_fma_f32 v[30:31], v[32:33], v[74:75], v[30:31]
	v_add_f32_e32 v9, 1.0, v9
	v_rcp_f32_e32 v35, v9
	v_pk_fma_f32 v[16:17], v[2:3], v[30:31], v[16:17] op_sel_hi:[0,1,1]
	v_lshlrev_b32_e32 v20, 16, v171
	v_and_b32_e32 v21, 0xffff0000, v171
	v_pk_mul_f32 v[18:19], v[34:35], v[18:19]
	v_lshlrev_b32_e32 v24, 16, v175
	v_pk_mul_f32 v[16:17], v[18:19], v[16:17]
	v_lshlrev_b32_e32 v18, 16, v173
	v_mul_f32_e32 v9, 0xbfb8aa3b, v18
	v_exp_f32_e32 v9, v9
	v_and_b32_e32 v25, 0xffff0000, v175
	v_and_b32_e32 v19, 0xffff0000, v173
	v_pk_add_f32 v[24:25], v[24:25], v[20:21] neg_lo:[0,1] neg_hi:[0,1]
	v_add_f32_e32 v9, 1.0, v9
	v_rcp_f32_e32 v30, v9
	v_pk_fma_f32 v[20:21], v[24:25], v[76:77], v[20:21]
	v_pk_mul_f32 v[24:25], v[62:63], v[8:9] op_sel_hi:[1,0]
	v_mul_f32_e32 v9, 0xbfb8aa3b, v19
	v_exp_f32_e32 v9, v9
	v_pk_fma_f32 v[22:23], v[22:23], v[24:25], v[26:27]
	v_lshlrev_b64 v[14:15], 11, v[176:177]
	v_pk_fma_f32 v[20:21], v[2:3], v[20:21], v[22:23] op_sel_hi:[0,1,1]
	v_add_f32_e32 v9, 1.0, v9
	v_rcp_f32_e32 v31, v9
	v_lshl_add_u64 v[14:15], s[6:7], 0, v[14:15]
	v_cvt_pk_bf16_f32 v16, v16, v17
	v_pk_mul_f32 v[18:19], v[30:31], v[18:19]
	s_nop 0
	v_pk_mul_f32 v[18:19], v[18:19], v[20:21]
	v_lshlrev_b32_e32 v20, 16, v154
	v_cvt_pk_bf16_f32 v17, v18, v19
	v_lshl_add_u64 v[18:19], v[14:15], 0, v[148:149]
	global_store_dwordx2 v[18:19], v[16:17], off offset:1536 sc0 sc1
	v_lshlrev_b32_e32 v16, 16, v150
	v_mul_f32_e32 v9, 0xbfb8aa3b, v16
	v_exp_f32_e32 v9, v9
	v_and_b32_e32 v17, 0xffff0000, v150
	v_lshlrev_b32_e32 v18, 16, v152
	v_and_b32_e32 v19, 0xffff0000, v152
	v_add_f32_e32 v9, 1.0, v9
	v_rcp_f32_e32 v22, v9
	v_pk_mul_f32 v[12:13], v[12:13], v[8:9] op_sel_hi:[1,0]
	v_mul_f32_e32 v9, 0xbfb8aa3b, v17
	v_exp_f32_e32 v9, v9
	v_and_b32_e32 v21, 0xffff0000, v154
	v_pk_add_f32 v[20:21], v[20:21], v[18:19] neg_lo:[0,1] neg_hi:[0,1]
	v_pk_fma_f32 v[12:13], v[52:53], v[12:13], v[56:57]
	v_add_f32_e32 v9, 1.0, v9
	v_rcp_f32_e32 v23, v9
	v_pk_fma_f32 v[18:19], v[20:21], v[86:87], v[18:19]
	v_lshlrev_b32_e32 v20, 16, v155
	v_pk_fma_f32 v[12:13], v[2:3], v[18:19], v[12:13] op_sel_hi:[0,1,1]
	v_pk_mul_f32 v[16:17], v[22:23], v[16:17]
	v_lshlrev_b32_e32 v18, 16, v153
	v_pk_mul_f32 v[12:13], v[16:17], v[12:13]
	v_lshlrev_b32_e32 v16, 16, v151
	v_mul_f32_e32 v9, 0xbfb8aa3b, v16
	v_exp_f32_e32 v9, v9
	v_and_b32_e32 v19, 0xffff0000, v153
	v_and_b32_e32 v21, 0xffff0000, v155
	v_and_b32_e32 v17, 0xffff0000, v151
	v_add_f32_e32 v9, 1.0, v9
	v_pk_add_f32 v[20:21], v[20:21], v[18:19] neg_lo:[0,1] neg_hi:[0,1]
	v_rcp_f32_e32 v22, v9
	v_pk_fma_f32 v[18:19], v[20:21], v[88:89], v[18:19]
	v_pk_mul_f32 v[20:21], v[42:43], v[8:9] op_sel_hi:[1,0]
	v_mul_f32_e32 v9, 0xbfb8aa3b, v17
	v_exp_f32_e32 v9, v9
	v_pk_fma_f32 v[20:21], v[54:55], v[20:21], v[58:59]
	v_add_f32_e32 v9, 1.0, v9
	v_rcp_f32_e32 v23, v9
	v_pk_fma_f32 v[18:19], v[2:3], v[18:19], v[20:21] op_sel_hi:[0,1,1]
	v_pk_mul_f32 v[16:17], v[22:23], v[16:17]
	s_nop 0
	v_pk_mul_f32 v[16:17], v[16:17], v[18:19]
	v_cvt_pk_bf16_f32 v18, v12, v13
	v_lshl_add_u64 v[12:13], v[14:15], 0, v[196:197]
	v_lshlrev_b32_e32 v14, 16, v142
	v_mul_f32_e32 v9, 0xbfb8aa3b, v14
	v_exp_f32_e32 v9, v9
	v_cvt_pk_bf16_f32 v19, v16, v17
	global_store_dwordx2 v[12:13], v[18:19], off offset:1568 sc0 sc1
	v_lshlrev_b32_e32 v16, 16, v144
	v_and_b32_e32 v17, 0xffff0000, v144
	v_lshlrev_b32_e32 v18, 16, v146
	v_and_b32_e32 v19, 0xffff0000, v146
	v_and_b32_e32 v15, 0xffff0000, v142
	v_add_f32_e32 v9, 1.0, v9
	v_pk_add_f32 v[18:19], v[18:19], v[16:17] neg_lo:[0,1] neg_hi:[0,1]
	v_rcp_f32_e32 v20, v9
	v_pk_fma_f32 v[16:17], v[18:19], v[98:99], v[16:17]
	v_pk_mul_f32 v[18:19], v[28:29], v[8:9] op_sel_hi:[1,0]
	v_mul_f32_e32 v9, 0xbfb8aa3b, v15
	v_exp_f32_e32 v9, v9
	v_pk_fma_f32 v[18:19], v[78:79], v[18:19], v[82:83]
	v_add_f32_e32 v9, 1.0, v9
	v_rcp_f32_e32 v21, v9
	v_pk_fma_f32 v[16:17], v[2:3], v[16:17], v[18:19] op_sel_hi:[0,1,1]
	v_lshlrev_b32_e32 v18, 16, v145
	v_and_b32_e32 v19, 0xffff0000, v145
	v_pk_mul_f32 v[14:15], v[20:21], v[14:15]
	v_lshlrev_b32_e32 v20, 16, v147
	v_pk_mul_f32 v[14:15], v[14:15], v[16:17]
	v_lshlrev_b32_e32 v16, 16, v143
	v_mul_f32_e32 v9, 0xbfb8aa3b, v16
	v_exp_f32_e32 v9, v9
	v_and_b32_e32 v17, 0xffff0000, v143
	v_and_b32_e32 v21, 0xffff0000, v147
	v_pk_add_f32 v[20:21], v[20:21], v[18:19] neg_lo:[0,1] neg_hi:[0,1]
	v_add_f32_e32 v9, 1.0, v9
	v_rcp_f32_e32 v22, v9
	v_pk_mul_f32 v[10:11], v[10:11], v[8:9] op_sel_hi:[1,0]
	v_mul_f32_e32 v9, 0xbfb8aa3b, v17
	v_exp_f32_e32 v9, v9
	v_pk_fma_f32 v[18:19], v[20:21], v[100:101], v[18:19]
	v_pk_fma_f32 v[10:11], v[80:81], v[10:11], v[84:85]
	v_cvt_pk_bf16_f32 v14, v14, v15
	v_add_f32_e32 v9, 1.0, v9
	v_rcp_f32_e32 v23, v9
	v_pk_fma_f32 v[10:11], v[2:3], v[18:19], v[10:11] op_sel_hi:[0,1,1]
	v_pk_mul_f32 v[16:17], v[22:23], v[16:17]
	s_nop 0
	v_pk_mul_f32 v[10:11], v[16:17], v[10:11]
	v_lshlrev_b32_e32 v16, 16, v140
	v_cvt_pk_bf16_f32 v15, v10, v11
	v_lshlrev_b32_e32 v10, 16, v136
	v_mul_f32_e32 v9, 0xbfb8aa3b, v10
	v_exp_f32_e32 v9, v9
	v_and_b32_e32 v11, 0xffff0000, v136
	global_store_dwordx2 v[12:13], v[14:15], off offset:1600 sc0 sc1
	v_lshlrev_b32_e32 v14, 16, v138
	v_add_f32_e32 v9, 1.0, v9
	v_rcp_f32_e32 v18, v9
	v_pk_mul_f32 v[4:5], v[4:5], v[8:9] op_sel_hi:[1,0]
	v_mul_f32_e32 v9, 0xbfb8aa3b, v11
	v_exp_f32_e32 v9, v9
	v_and_b32_e32 v15, 0xffff0000, v138
	v_and_b32_e32 v17, 0xffff0000, v140
	v_pk_add_f32 v[16:17], v[16:17], v[14:15] neg_lo:[0,1] neg_hi:[0,1]
	v_add_f32_e32 v9, 1.0, v9
	v_rcp_f32_e32 v19, v9
	v_pk_fma_f32 v[14:15], v[16:17], v[102:103], v[14:15]
	v_pk_fma_f32 v[4:5], v[90:91], v[4:5], v[94:95]
	v_lshlrev_b32_e32 v16, 16, v141
	v_pk_fma_f32 v[4:5], v[2:3], v[14:15], v[4:5] op_sel_hi:[0,1,1]
	v_pk_mul_f32 v[10:11], v[18:19], v[10:11]
	v_lshlrev_b32_e32 v14, 16, v139
	v_pk_mul_f32 v[4:5], v[10:11], v[4:5]
	v_lshlrev_b32_e32 v10, 16, v137
	v_mul_f32_e32 v9, 0xbfb8aa3b, v10
	v_exp_f32_e32 v9, v9
	v_and_b32_e32 v15, 0xffff0000, v139
	v_and_b32_e32 v17, 0xffff0000, v141
	v_pk_add_f32 v[16:17], v[16:17], v[14:15] neg_lo:[0,1] neg_hi:[0,1]
	v_add_f32_e32 v9, 1.0, v9
	v_pk_mul_f32 v[6:7], v[6:7], v[8:9] op_sel_hi:[1,0]
	v_and_b32_e32 v11, 0xffff0000, v137
	v_pk_fma_f32 v[14:15], v[16:17], v[104:105], v[14:15]
	v_pk_fma_f32 v[6:7], v[92:93], v[6:7], v[96:97]
	v_rcp_f32_e32 v18, v9
	v_pk_fma_f32 v[6:7], v[2:3], v[14:15], v[6:7] op_sel_hi:[0,1,1]
	v_mul_f32_e32 v2, 0xbfb8aa3b, v11
	v_exp_f32_e32 v2, v2
	v_cvt_pk_bf16_f32 v4, v4, v5
	v_add_f32_e32 v2, 1.0, v2
	v_rcp_f32_e32 v19, v2
	s_nop 0
	v_pk_mul_f32 v[8:9], v[18:19], v[10:11]
	s_nop 0
	v_pk_mul_f32 v[6:7], v[8:9], v[6:7]
	s_nop 0
	v_cvt_pk_bf16_f32 v5, v6, v7
	global_store_dwordx2 v[12:13], v[4:5], off offset:1632 sc0 sc1

.LBB0_1011:
	s_andn2_b64 vcc, exec, s[4:5]
	s_cbranch_vccnz .LBB0_952
	s_mov_b64 s[4:5], -1
	s_cmp_eq_u32 s23, 1
	s_mul_hi_i32 s26, s20, 0x1100000
	s_mul_i32 s27, s20, 0x1100000
	v_lshlrev_b32_e32 v2, 1, v120
	v_lshlrev_b32_e32 v136, 1, v106
	v_lshlrev_b32_e32 v104, 1, v112
	s_cbranch_scc1 .LBB0_1014
	s_ashr_i32 s21, s20, 31
	s_add_u32 s29, s38, s27
	s_addc_u32 s34, s39, s26
	s_lshl_b64 s[4:5], s[20:21], 22
	s_add_u32 s21, s0, s4
	s_addc_u32 s28, s1, s5
	s_ashr_i32 s25, s24, 31
	s_lshl_b32 s4, s55, 6
	s_lshl_b64 s[6:7], s[24:25], 13
	s_ashr_i32 s23, s22, 31
	s_lshl_b64 s[30:31], s[24:25], 18
	s_add_u32 s5, s52, s30
	s_addc_u32 s25, s53, s31
	s_lshl_b64 s[30:31], s[22:23], 14
	s_add_u32 s30, s5, s30
	s_addc_u32 s31, s25, s31
	v_mov_b32_e32 v137, v3
	v_lshl_add_u64 v[4:5], s[30:31], 0, v[2:3]
	v_lshl_add_u64 v[6:7], v[4:5], 0, v[136:137]
	v_add_co_u32_e32 v10, vcc, s63, v6
	s_mov_b64 s[30:31], 0x2000
	s_nop 0
	v_addc_co_u32_e32 v11, vcc, 0, v7, vcc
	v_lshl_add_u64 v[8:9], v[6:7], 0, s[30:31]
	global_load_dwordx4 v[92:95], v[10:11], off
	global_load_dwordx4 v[88:91], v[8:9], off offset:64
	v_mov_b32_e32 v105, v3
	v_add_co_u32_e32 v10, vcc, s57, v6
	v_lshl_add_u64 v[4:5], v[4:5], 0, v[104:105]
	s_mov_b64 s[30:31], 0x6000
	v_addc_co_u32_e32 v11, vcc, 0, v7, vcc
	global_load_dwordx2 v[78:79], v[4:5], off
	global_load_dwordx2 v[80:81], v[4:5], off offset:32
	global_load_dwordx2 v[84:85], v[4:5], off offset:64
	global_load_dwordx2 v[202:203], v[4:5], off offset:96
	v_lshl_add_u64 v[8:9], v[6:7], 0, s[30:31]
	global_load_dwordx4 v[72:75], v[10:11], off
	global_load_dwordx4 v[68:71], v[8:9], off offset:64
	v_add_co_u32_e32 v10, vcc, s65, v4
	v_lshl_add_u64 v[8:9], v[4:5], 0, s[50:51]
	s_nop 0
	v_addc_co_u32_e32 v11, vcc, 0, v5, vcc
	global_load_dwordx2 v[98:99], v[10:11], off
	global_load_dwordx2 v[96:97], v[8:9], off offset:32
	global_load_dwordx2 v[200:201], v[8:9], off offset:64
	global_load_dwordx2 v[188:189], v[8:9], off offset:96
	v_add_co_u32_e32 v10, vcc, s59, v6
	s_mov_b64 s[30:31], 0xa000
	s_nop 0
	v_addc_co_u32_e32 v11, vcc, 0, v7, vcc
	v_lshl_add_u64 v[8:9], v[6:7], 0, s[30:31]
	global_load_dwordx4 v[64:67], v[10:11], off
	global_load_dwordx4 v[60:63], v[8:9], off offset:64
	s_mov_b64 s[30:31], 0x8000
	v_add_co_u32_e32 v10, vcc, s58, v4
	v_lshl_add_u64 v[8:9], v[4:5], 0, s[30:31]
	s_nop 0
	v_addc_co_u32_e32 v11, vcc, 0, v5, vcc
	s_mov_b64 s[30:31], 0xe000
	global_load_dwordx2 v[186:187], v[10:11], off
	global_load_dwordx2 v[182:183], v[8:9], off offset:32
	global_load_dwordx2 v[178:179], v[8:9], off offset:64
	global_load_dwordx2 v[176:177], v[8:9], off offset:96
	v_lshl_add_u64 v[8:9], v[6:7], 0, s[30:31]
	v_add_co_u32_e32 v6, vcc, s61, v6
	s_mov_b64 s[30:31], 0xc000
	s_nop 0
	v_addc_co_u32_e32 v7, vcc, 0, v7, vcc
	global_load_dwordx4 v[24:27], v[6:7], off
	global_load_dwordx4 v[20:23], v[8:9], off offset:64
	v_lshl_add_u64 v[6:7], v[4:5], 0, s[30:31]
	v_add_co_u32_e32 v4, vcc, s60, v4
	s_ashr_i32 s5, s4, 31
	s_nop 0
	v_addc_co_u32_e32 v5, vcc, 0, v5, vcc
	global_load_dwordx2 v[168:169], v[4:5], off
	global_load_dwordx2 v[154:155], v[6:7], off offset:32
	global_load_dwordx2 v[152:153], v[6:7], off offset:64
	global_load_dwordx2 v[150:151], v[6:7], off offset:96
	v_lshl_add_u64 v[4:5], v[118:119], 0, s[6:7]
	global_load_dwordx4 v[56:59], v[4:5], off
	global_load_dwordx4 v[52:55], v[4:5], off offset:64
	global_load_dwordx4 v[48:51], v[4:5], off offset:2048
	global_load_dwordx4 v[44:47], v[4:5], off offset:2112
	v_add_co_u32_e32 v4, vcc, s66, v4
	s_lshl_b64 s[4:5], s[4:5], 1
	s_nop 0
	v_addc_co_u32_e32 v5, vcc, 0, v5, vcc
	global_load_dwordx4 v[40:43], v[4:5], off
	global_load_dwordx4 v[36:39], v[4:5], off offset:64
	global_load_dwordx4 v[32:35], v[4:5], off offset:2048
	global_load_dwordx4 v[28:31], v[4:5], off offset:2112
	s_add_u32 s6, s29, s4
	s_addc_u32 s7, s34, s5
	v_lshl_add_u64 v[4:5], s[6:7], 0, v[104:105]
	s_mov_b64 s[6:7], 0x1800
	s_lshl_b32 s23, s54, 6
	v_lshl_add_u64 v[4:5], v[4:5], 0, s[6:7]
	v_or_b32_e32 v210, s23, v0
	v_mad_i64_i32 v[6:7], s[6:7], v210, s64, v[4:5]
	global_load_dwordx2 v[208:209], v[6:7], off
	global_load_dwordx2 v[212:213], v[6:7], off offset:32
	global_load_dwordx2 v[102:103], v[6:7], off offset:64
	global_load_dwordx2 v[100:101], v[6:7], off offset:96
	v_and_b32_e32 v77, 64, v234
	v_xor_b32_e32 v76, 16, v234
	v_add_u32_e32 v77, 64, v77
	v_cmp_lt_i32_e32 vcc, v76, v77
	s_add_u32 s4, s21, s4
	s_addc_u32 s5, s28, s5
	v_cndmask_b32_e32 v76, v234, v76, vcc
	v_lshlrev_b32_e32 v131, 2, v76
	v_xor_b32_e32 v76, 32, v234
	v_cmp_lt_i32_e32 vcc, v76, v77
	v_lshl_add_u64 v[148:149], s[4:5], 0, v[104:105]
	v_ashrrev_i32_e32 v211, 31, v210
	v_cndmask_b32_e32 v76, v234, v76, vcc
	v_lshlrev_b32_e32 v129, 2, v76
	v_add_u32_e32 v198, s23, v1
	v_mad_i64_i32 v[6:7], s[6:7], v198, s64, v[4:5]
	v_add_u32_e32 v184, s23, v113
	v_add_u32_e32 v146, s23, v121
	global_load_dwordx2 v[196:197], v[6:7], off
	global_load_dwordx2 v[194:195], v[6:7], off offset:32
	global_load_dwordx2 v[192:193], v[6:7], off offset:64
	global_load_dwordx2 v[190:191], v[6:7], off offset:96
	v_mad_i64_i32 v[6:7], s[6:7], v184, s64, v[4:5]
	s_waitcnt vmcnt(37)
	v_lshlrev_b32_e32 v76, 16, v78
	v_and_b32_e32 v77, 0xffff0000, v78
	v_lshlrev_b32_e32 v78, 16, v79
	v_and_b32_e32 v79, 0xffff0000, v79
	s_waitcnt vmcnt(36)
	v_lshlrev_b32_e32 v206, 16, v81
	v_and_b32_e32 v207, 0xffff0000, v81
	s_waitcnt vmcnt(15)
	v_mfma_f32_16x16x32_bf16 v[76:79], v[56:59], v[92:95], v[76:79]
	v_mad_i64_i32 v[4:5], s[6:7], v146, s64, v[4:5]
	global_load_dwordx2 v[180:181], v[6:7], off
	global_load_dwordx2 v[174:175], v[6:7], off offset:32
	global_load_dwordx2 v[172:173], v[6:7], off offset:64
	global_load_dwordx2 v[170:171], v[6:7], off offset:96
	s_waitcnt vmcnt(18)
	v_mfma_f32_16x16x32_bf16 v[76:79], v[52:55], v[88:91], v[76:79]
	global_load_dwordx2 v[144:145], v[4:5], off
	global_load_dwordx2 v[142:143], v[4:5], off offset:32
	global_load_dwordx2 v[140:141], v[4:5], off offset:64
	global_load_dwordx2 v[138:139], v[4:5], off offset:96
	global_load_dwordx4 v[16:19], v[124:125], off
	global_load_dwordx4 v[12:15], v[124:125], off offset:64
	global_load_dwordx4 v[8:11], v[124:125], off offset:128
	s_nop 0
	global_load_dwordx4 v[4:7], v[124:125], off offset:192
	v_lshlrev_b32_e32 v224, 16, v189
	v_and_b32_e32 v225, 0xffff0000, v189
	v_pk_mul_f32 v[82:83], v[78:79], v[78:79]
	v_pk_mul_f32 v[86:87], v[76:77], v[76:77]
	v_ashrrev_i32_e32 v199, 31, v198
	v_pk_mov_b32 v[204:205], v[86:87], v[82:83] op_sel:[1,0]
	v_mov_b32_e32 v87, v83
	v_pk_add_f32 v[214:215], v[204:205], v[86:87]
	v_lshlrev_b32_e32 v204, 16, v80
	v_and_b32_e32 v205, 0xffff0000, v80
	v_ashrrev_i32_e32 v185, 31, v184
	v_ashrrev_i32_e32 v147, 31, v146
	s_waitcnt vmcnt(25)
	v_mfma_f32_16x16x32_bf16 v[80:83], v[48:51], v[92:95], v[204:207]
	s_waitcnt vmcnt(24)
	v_mfma_f32_16x16x32_bf16 v[80:83], v[44:47], v[88:91], v[80:83]
	s_nop 7
	v_pk_mul_f32 v[86:87], v[82:83], v[82:83]
	v_pk_mul_f32 v[204:205], v[80:81], v[80:81]
	s_nop 0
	v_pk_mov_b32 v[206:207], v[204:205], v[86:87] op_sel:[1,0]
	v_mov_b32_e32 v205, v87
	v_pk_add_f32 v[216:217], v[206:207], v[204:205]
	v_lshlrev_b32_e32 v204, 16, v84
	v_and_b32_e32 v205, 0xffff0000, v84
	v_lshlrev_b32_e32 v206, 16, v85
	v_and_b32_e32 v207, 0xffff0000, v85
	s_waitcnt vmcnt(23)
	s_nop 0
	v_mfma_f32_16x16x32_bf16 v[84:87], v[40:43], v[92:95], v[204:207]
	s_nop 2
	v_lshlrev_b32_e32 v204, 16, v202
	v_and_b32_e32 v205, 0xffff0000, v202
	v_lshlrev_b32_e32 v206, 16, v203
	v_and_b32_e32 v207, 0xffff0000, v203
	s_waitcnt vmcnt(22)
	v_mfma_f32_16x16x32_bf16 v[84:87], v[36:39], v[88:91], v[84:87]
	s_waitcnt vmcnt(21)
	v_mfma_f32_16x16x32_bf16 v[92:95], v[32:35], v[92:95], v[204:207]
	s_waitcnt vmcnt(20)
	v_mfma_f32_16x16x32_bf16 v[88:91], v[28:31], v[88:91], v[92:95]
	s_nop 3
	v_mul_f32_e32 v202, v87, v87
	v_pk_fma_f32 v[202:203], v[86:87], v[86:87], v[202:203] op_sel_hi:[1,1,0]
	v_pk_add_f32 v[92:93], v[214:215], v[214:215] op_sel:[0,1] op_sel_hi:[1,0]
	s_nop 0
	v_mul_f32_e32 v94, v88, v88
	v_mul_f32_e32 v105, v89, v89
	v_mov_b32_e32 v93, v94
	v_pk_add_f32 v[94:95], v[216:217], v[216:217] op_sel:[0,1] op_sel_hi:[1,0]
	v_mul_f32_e32 v133, v90, v90
	v_mov_b32_e32 v95, v105
	v_pk_add_f32 v[92:93], v[92:93], v[94:95]
	v_mul_f32_e32 v94, v85, v85
	v_mul_f32_e32 v135, v91, v91
	v_pk_fma_f32 v[94:95], v[84:85], v[84:85], v[94:95] op_sel_hi:[1,1,0]
	v_mov_b32_e32 v203, v135
	v_mov_b32_e32 v95, v133
	v_pk_add_f32 v[94:95], v[94:95], v[202:203]
	s_nop 0
	v_pk_add_f32 v[206:207], v[92:93], v[94:95]
	v_lshlrev_b64 v[92:93], 11, v[210:211]
	v_lshl_add_u64 v[202:203], v[148:149], 0, v[92:93]
	s_waitcnt vmcnt(19)
	v_lshlrev_b32_e32 v92, 16, v208
	v_and_b32_e32 v93, 0xffff0000, v208
	v_mul_f32_e32 v94, 0xbfb8aa3b, v92
	v_mul_f32_e32 v95, 0xbfb8aa3b, v93
	v_exp_f32_e32 v94, v94
	v_exp_f32_e32 v95, v95
	v_add_f32_e32 v94, 1.0, v94
	v_add_f32_e32 v95, 1.0, v95
	v_rcp_f32_e32 v94, v94
	v_rcp_f32_e32 v95, v95
	s_nop 0
	v_pk_mul_f32 v[204:205], v[94:95], v[92:93]
	v_lshlrev_b32_e32 v92, 16, v209
	v_and_b32_e32 v93, 0xffff0000, v209
	v_mul_f32_e32 v94, 0xbfb8aa3b, v92
	v_mul_f32_e32 v95, 0xbfb8aa3b, v93
	v_exp_f32_e32 v94, v94
	v_exp_f32_e32 v95, v95
	v_add_f32_e32 v94, 1.0, v94
	v_add_f32_e32 v95, 1.0, v95
	v_rcp_f32_e32 v94, v94
	v_rcp_f32_e32 v95, v95
	s_nop 0
	v_pk_mul_f32 v[208:209], v[94:95], v[92:93]
	s_waitcnt vmcnt(18)
	v_lshlrev_b32_e32 v92, 16, v212
	v_and_b32_e32 v93, 0xffff0000, v212
	v_mul_f32_e32 v94, 0xbfb8aa3b, v92
	v_mul_f32_e32 v95, 0xbfb8aa3b, v93
	v_exp_f32_e32 v94, v94
	v_exp_f32_e32 v95, v95
	v_add_f32_e32 v94, 1.0, v94
	v_add_f32_e32 v95, 1.0, v95
	v_rcp_f32_e32 v94, v94
	v_rcp_f32_e32 v95, v95
	s_nop 0
	v_pk_mul_f32 v[210:211], v[94:95], v[92:93]
	v_lshlrev_b32_e32 v92, 16, v213
	v_and_b32_e32 v93, 0xffff0000, v213
	v_mul_f32_e32 v94, 0xbfb8aa3b, v92
	v_mul_f32_e32 v95, 0xbfb8aa3b, v93
	v_exp_f32_e32 v94, v94
	v_exp_f32_e32 v95, v95
	v_add_f32_e32 v94, 1.0, v94
	v_add_f32_e32 v95, 1.0, v95
	v_rcp_f32_e32 v94, v94
	v_rcp_f32_e32 v95, v95
	s_nop 0
	v_pk_mul_f32 v[212:213], v[94:95], v[92:93]
	s_waitcnt vmcnt(17)
	v_lshlrev_b32_e32 v92, 16, v102
	v_and_b32_e32 v93, 0xffff0000, v102
	v_mul_f32_e32 v94, 0xbfb8aa3b, v92
	v_mul_f32_e32 v95, 0xbfb8aa3b, v93
	v_exp_f32_e32 v94, v94
	v_exp_f32_e32 v95, v95
	v_add_f32_e32 v94, 1.0, v94
	v_add_f32_e32 v95, 1.0, v95
	v_rcp_f32_e32 v94, v94
	v_rcp_f32_e32 v95, v95
	s_nop 0
	v_pk_mul_f32 v[214:215], v[94:95], v[92:93]
	v_lshlrev_b32_e32 v92, 16, v103
	v_and_b32_e32 v93, 0xffff0000, v103
	v_mul_f32_e32 v94, 0xbfb8aa3b, v92
	v_mul_f32_e32 v95, 0xbfb8aa3b, v93
	v_exp_f32_e32 v94, v94
	v_exp_f32_e32 v95, v95
	v_add_f32_e32 v94, 1.0, v94
	v_add_f32_e32 v95, 1.0, v95
	v_rcp_f32_e32 v94, v94
	v_rcp_f32_e32 v95, v95
	s_nop 0
	v_pk_mul_f32 v[216:217], v[94:95], v[92:93]
	s_waitcnt vmcnt(16)
	v_lshlrev_b32_e32 v92, 16, v100
	v_and_b32_e32 v93, 0xffff0000, v100
	v_mul_f32_e32 v94, 0xbfb8aa3b, v92
	v_mul_f32_e32 v95, 0xbfb8aa3b, v93
	v_exp_f32_e32 v94, v94
	v_exp_f32_e32 v95, v95
	v_add_f32_e32 v94, 1.0, v94
	v_add_f32_e32 v95, 1.0, v95
	v_rcp_f32_e32 v94, v94
	v_rcp_f32_e32 v95, v95
	s_nop 0
	v_pk_mul_f32 v[218:219], v[94:95], v[92:93]
	v_lshlrev_b32_e32 v92, 16, v101
	v_and_b32_e32 v93, 0xffff0000, v101
	v_mul_f32_e32 v94, 0xbfb8aa3b, v92
	v_mul_f32_e32 v95, 0xbfb8aa3b, v93
	v_exp_f32_e32 v94, v94
	v_exp_f32_e32 v95, v95
	v_add_f32_e32 v94, 1.0, v94
	v_add_f32_e32 v95, 1.0, v95
	v_rcp_f32_e32 v94, v94
	v_rcp_f32_e32 v95, v95
	s_nop 0
	v_pk_mul_f32 v[220:221], v[94:95], v[92:93]
	v_lshlrev_b32_e32 v92, 16, v98
	v_and_b32_e32 v93, 0xffff0000, v98
	v_lshlrev_b32_e32 v94, 16, v99
	v_and_b32_e32 v95, 0xffff0000, v99
	s_nop 1
	v_mfma_f32_16x16x32_bf16 v[92:95], v[56:59], v[72:75], v[92:95]
	v_mfma_f32_16x16x32_bf16 v[100:103], v[52:55], v[68:71], v[92:95]
	s_nop 7
	v_pk_mul_f32 v[92:93], v[102:103], v[102:103]
	v_pk_mul_f32 v[94:95], v[100:101], v[100:101]
	s_nop 0
	v_pk_mov_b32 v[98:99], v[94:95], v[92:93] op_sel:[1,0]
	v_mov_b32_e32 v95, v93
	v_pk_add_f32 v[226:227], v[98:99], v[94:95]
	v_lshlrev_b32_e32 v92, 16, v96
	v_and_b32_e32 v93, 0xffff0000, v96
	v_lshlrev_b32_e32 v94, 16, v97
	v_and_b32_e32 v95, 0xffff0000, v97
	s_nop 1
	v_mfma_f32_16x16x32_bf16 v[92:95], v[48:51], v[72:75], v[92:95]
	v_mfma_f32_16x16x32_bf16 v[96:99], v[44:47], v[68:71], v[92:95]
	s_nop 7
	v_pk_mul_f32 v[92:93], v[98:99], v[98:99]
	v_pk_mul_f32 v[94:95], v[96:97], v[96:97]
	s_nop 0
	v_pk_mov_b32 v[222:223], v[94:95], v[92:93] op_sel:[1,0]
	v_mov_b32_e32 v95, v93
	v_pk_add_f32 v[228:229], v[222:223], v[94:95]
	v_lshlrev_b32_e32 v92, 16, v200
	v_and_b32_e32 v93, 0xffff0000, v200
	v_lshlrev_b32_e32 v94, 16, v201
	v_and_b32_e32 v95, 0xffff0000, v201
	v_lshlrev_b32_e32 v222, 16, v188
	v_and_b32_e32 v223, 0xffff0000, v188
	v_mfma_f32_16x16x32_bf16 v[92:95], v[40:43], v[72:75], v[92:95]
	s_nop 0
	v_mfma_f32_16x16x32_bf16 v[72:75], v[32:35], v[72:75], v[222:225]
	v_mfma_f32_16x16x32_bf16 v[92:95], v[36:39], v[68:71], v[92:95]
	v_mfma_f32_16x16x32_bf16 v[68:71], v[28:31], v[68:71], v[72:75]
	s_nop 5
	v_add_f32_e64 v72, v226, v227
	v_add_f32_e64 v73, v227, v226
	v_mul_f32_e32 v188, v95, v95
	v_mul_f32_e32 v74, v68, v68
	v_mul_f32_e32 v105, v69, v69
	v_mov_b32_e32 v73, v74
	v_pk_add_f32 v[74:75], v[228:229], v[228:229] op_sel:[0,1] op_sel_hi:[1,0]
	v_mul_f32_e32 v133, v70, v70
	v_mov_b32_e32 v75, v105
	v_pk_add_f32 v[72:73], v[72:73], v[74:75]
	v_mul_f32_e32 v74, v93, v93
	v_mul_f32_e32 v135, v71, v71
	v_pk_fma_f32 v[74:75], v[92:93], v[92:93], v[74:75] op_sel_hi:[1,1,0]
	v_pk_fma_f32 v[188:189], v[94:95], v[94:95], v[188:189] op_sel_hi:[1,1,0]
	v_mov_b32_e32 v75, v133
	v_mov_b32_e32 v189, v135
	v_pk_add_f32 v[74:75], v[74:75], v[188:189]
	v_mov_b64_e32 v[188:189], s[82:83]
	v_pk_add_f32 v[72:73], v[72:73], v[74:75]
	v_mov_b32_e32 v75, v206
	v_mov_b32_e32 v74, v72
	v_mov_b32_e32 v206, v73
	v_pk_add_f32 v[72:73], v[74:75], v[206:207]
	ds_bpermute_b32 v75, v131, v73
	ds_bpermute_b32 v74, v131, v72
	s_waitcnt lgkmcnt(0)
	v_pk_add_f32 v[72:73], v[72:73], v[74:75]
	ds_bpermute_b32 v75, v129, v73
	ds_bpermute_b32 v74, v129, v72
	s_waitcnt lgkmcnt(0)
	v_pk_add_f32 v[72:73], v[72:73], v[74:75]
	s_nop 0
	v_pk_fma_f32 v[72:73], v[72:73], s[84:85], v[188:189] op_sel_hi:[1,0,0]
	s_nop 0
	v_mul_f32_e32 v74, 0x4b800000, v73
	v_cmp_gt_f32_e64 s[4:5], s75, v73
	v_cmp_gt_f32_e32 vcc, s75, v72
	s_nop 0
	v_cndmask_b32_e64 v73, v73, v74, s[4:5]
	v_rsq_f32_e32 v73, v73
	s_nop 0
	v_mul_f32_e32 v74, 0x45800000, v73
	v_cndmask_b32_e64 v74, v73, v74, s[4:5]
	v_pk_mul_f32 v[76:77], v[76:77], v[74:75] op_sel_hi:[1,0]
	v_pk_mul_f32 v[78:79], v[78:79], v[74:75] op_sel_hi:[1,0]
	s_waitcnt vmcnt(3)
	v_pk_mul_f32 v[76:77], v[16:17], v[76:77]
	v_pk_mul_f32 v[78:79], v[18:19], v[78:79]
	v_pk_mul_f32 v[76:77], v[204:205], v[76:77]
	v_pk_mul_f32 v[78:79], v[208:209], v[78:79]
	v_cvt_pk_bf16_f32 v76, v76, v77
	v_cvt_pk_bf16_f32 v77, v78, v79
	global_store_dwordx2 v[202:203], v[76:77], off sc0 sc1
	v_pk_mul_f32 v[76:77], v[80:81], v[74:75] op_sel_hi:[1,0]
	v_pk_mul_f32 v[78:79], v[82:83], v[74:75] op_sel_hi:[1,0]
	s_waitcnt vmcnt(3)
	v_pk_mul_f32 v[76:77], v[12:13], v[76:77]
	v_pk_mul_f32 v[78:79], v[14:15], v[78:79]
	v_pk_mul_f32 v[76:77], v[210:211], v[76:77]
	v_pk_mul_f32 v[78:79], v[212:213], v[78:79]
	v_cvt_pk_bf16_f32 v76, v76, v77
	v_cvt_pk_bf16_f32 v77, v78, v79
	global_store_dwordx2 v[202:203], v[76:77], off offset:32 sc0 sc1
	v_pk_mul_f32 v[76:77], v[84:85], v[74:75] op_sel_hi:[1,0]
	v_pk_mul_f32 v[78:79], v[86:87], v[74:75] op_sel_hi:[1,0]
	s_waitcnt vmcnt(3)
	v_pk_mul_f32 v[76:77], v[8:9], v[76:77]
	v_pk_mul_f32 v[78:79], v[10:11], v[78:79]
	v_pk_mul_f32 v[76:77], v[214:215], v[76:77]
	v_pk_mul_f32 v[78:79], v[216:217], v[78:79]
	v_cvt_pk_bf16_f32 v76, v76, v77
	v_cvt_pk_bf16_f32 v77, v78, v79
	global_store_dwordx2 v[202:203], v[76:77], off offset:64 sc0 sc1
	v_pk_mul_f32 v[76:77], v[88:89], v[74:75] op_sel_hi:[1,0]
	v_pk_mul_f32 v[74:75], v[90:91], v[74:75] op_sel_hi:[1,0]
	s_waitcnt vmcnt(3)
	v_pk_mul_f32 v[76:77], v[4:5], v[76:77]
	v_pk_mul_f32 v[74:75], v[6:7], v[74:75]
	v_pk_mul_f32 v[76:77], v[218:219], v[76:77]
	v_pk_mul_f32 v[74:75], v[220:221], v[74:75]
	v_cvt_pk_bf16_f32 v76, v76, v77
	v_cvt_pk_bf16_f32 v77, v74, v75
	v_mul_f32_e32 v73, 0x4b800000, v72
	global_store_dwordx2 v[202:203], v[76:77], off offset:96 sc0 sc1
	v_cndmask_b32_e32 v72, v72, v73, vcc
	v_lshlrev_b32_e32 v76, 16, v196
	v_rsq_f32_e32 v72, v72
	v_mul_f32_e32 v75, 0xbfb8aa3b, v76
	v_exp_f32_e32 v75, v75
	v_and_b32_e32 v77, 0xffff0000, v196
	v_mul_f32_e32 v73, 0x45800000, v72
	v_cndmask_b32_e32 v74, v72, v73, vcc
	v_add_f32_e32 v75, 1.0, v75
	v_rcp_f32_e32 v78, v75
	v_pk_mul_f32 v[80:81], v[100:101], v[74:75] op_sel_hi:[1,0]
	v_mul_f32_e32 v75, 0xbfb8aa3b, v77
	v_exp_f32_e32 v75, v75
	v_pk_mul_f32 v[80:81], v[16:17], v[80:81]
	v_lshlrev_b64 v[72:73], 11, v[198:199]
	v_lshl_add_u64 v[72:73], v[148:149], 0, v[72:73]
	v_add_f32_e32 v75, 1.0, v75
	v_rcp_f32_e32 v79, v75
	s_nop 0
	v_pk_mul_f32 v[76:77], v[78:79], v[76:77]
	v_lshlrev_b32_e32 v78, 16, v197
	v_mul_f32_e32 v75, 0xbfb8aa3b, v78
	v_exp_f32_e32 v75, v75
	v_and_b32_e32 v79, 0xffff0000, v197
	v_pk_mul_f32 v[76:77], v[76:77], v[80:81]
	v_add_f32_e32 v75, 1.0, v75
	v_rcp_f32_e32 v80, v75
	v_pk_mul_f32 v[82:83], v[102:103], v[74:75] op_sel_hi:[1,0]
	v_mul_f32_e32 v75, 0xbfb8aa3b, v79
	v_exp_f32_e32 v75, v75
	v_pk_mul_f32 v[82:83], v[18:19], v[82:83]
	v_cvt_pk_bf16_f32 v76, v76, v77
	v_add_f32_e32 v75, 1.0, v75
	v_rcp_f32_e32 v81, v75
	s_nop 0
	v_pk_mul_f32 v[78:79], v[80:81], v[78:79]
	s_nop 0
	v_pk_mul_f32 v[78:79], v[78:79], v[82:83]
	s_nop 0
	v_cvt_pk_bf16_f32 v77, v78, v79
	global_store_dwordx2 v[72:73], v[76:77], off sc0 sc1
	v_lshlrev_b32_e32 v76, 16, v194
	v_mul_f32_e32 v75, 0xbfb8aa3b, v76
	v_exp_f32_e32 v75, v75
	v_and_b32_e32 v77, 0xffff0000, v194
	v_add_f32_e32 v75, 1.0, v75
	v_rcp_f32_e32 v78, v75
	v_pk_mul_f32 v[80:81], v[96:97], v[74:75] op_sel_hi:[1,0]
	v_mul_f32_e32 v75, 0xbfb8aa3b, v77
	v_exp_f32_e32 v75, v75
	v_pk_mul_f32 v[80:81], v[12:13], v[80:81]
	v_add_f32_e32 v75, 1.0, v75
	v_rcp_f32_e32 v79, v75
	s_nop 0
	v_pk_mul_f32 v[76:77], v[78:79], v[76:77]
	v_lshlrev_b32_e32 v78, 16, v195
	v_mul_f32_e32 v75, 0xbfb8aa3b, v78
	v_exp_f32_e32 v75, v75
	v_and_b32_e32 v79, 0xffff0000, v195
	v_pk_mul_f32 v[76:77], v[76:77], v[80:81]
	v_add_f32_e32 v75, 1.0, v75
	v_rcp_f32_e32 v80, v75
	v_pk_mul_f32 v[82:83], v[98:99], v[74:75] op_sel_hi:[1,0]
	v_mul_f32_e32 v75, 0xbfb8aa3b, v79
	v_exp_f32_e32 v75, v75
	v_pk_mul_f32 v[82:83], v[14:15], v[82:83]
	v_cvt_pk_bf16_f32 v76, v76, v77
	v_lshlrev_b32_e32 v98, 16, v169
	v_add_f32_e32 v75, 1.0, v75
	v_rcp_f32_e32 v81, v75
	v_and_b32_e32 v99, 0xffff0000, v169
	v_pk_mul_f32 v[78:79], v[80:81], v[78:79]
	s_nop 0
	v_pk_mul_f32 v[78:79], v[78:79], v[82:83]
	s_nop 0
	v_cvt_pk_bf16_f32 v77, v78, v79
	global_store_dwordx2 v[72:73], v[76:77], off offset:32 sc0 sc1
	v_lshlrev_b32_e32 v76, 16, v192
	v_mul_f32_e32 v75, 0xbfb8aa3b, v76
	v_exp_f32_e32 v75, v75
	v_and_b32_e32 v77, 0xffff0000, v192
	v_add_f32_e32 v75, 1.0, v75
	v_rcp_f32_e32 v78, v75
	v_pk_mul_f32 v[80:81], v[92:93], v[74:75] op_sel_hi:[1,0]
	v_mul_f32_e32 v75, 0xbfb8aa3b, v77
	v_exp_f32_e32 v75, v75
	v_pk_mul_f32 v[80:81], v[8:9], v[80:81]
	v_add_f32_e32 v75, 1.0, v75
	v_rcp_f32_e32 v79, v75
	s_nop 0
	v_pk_mul_f32 v[76:77], v[78:79], v[76:77]
	v_lshlrev_b32_e32 v78, 16, v193
	v_mul_f32_e32 v75, 0xbfb8aa3b, v78
	v_exp_f32_e32 v75, v75
	v_and_b32_e32 v79, 0xffff0000, v193
	v_pk_mul_f32 v[76:77], v[76:77], v[80:81]
	v_add_f32_e32 v75, 1.0, v75
	v_rcp_f32_e32 v80, v75
	v_pk_mul_f32 v[82:83], v[94:95], v[74:75] op_sel_hi:[1,0]
	v_mul_f32_e32 v75, 0xbfb8aa3b, v79
	v_exp_f32_e32 v75, v75
	v_pk_mul_f32 v[82:83], v[10:11], v[82:83]
	v_cvt_pk_bf16_f32 v76, v76, v77
	v_add_f32_e32 v75, 1.0, v75
	v_rcp_f32_e32 v81, v75
	s_nop 0
	v_pk_mul_f32 v[78:79], v[80:81], v[78:79]
	s_nop 0
	v_pk_mul_f32 v[78:79], v[78:79], v[82:83]
	v_lshlrev_b32_e32 v82, 16, v177
	v_cvt_pk_bf16_f32 v77, v78, v79
	global_store_dwordx2 v[72:73], v[76:77], off offset:64 sc0 sc1
	v_lshlrev_b32_e32 v76, 16, v190
	v_mul_f32_e32 v75, 0xbfb8aa3b, v76
	v_exp_f32_e32 v75, v75
	v_and_b32_e32 v77, 0xffff0000, v190
	v_and_b32_e32 v83, 0xffff0000, v177
	v_add_f32_e32 v75, 1.0, v75
	v_rcp_f32_e32 v78, v75
	v_pk_mul_f32 v[68:69], v[68:69], v[74:75] op_sel_hi:[1,0]
	v_mul_f32_e32 v75, 0xbfb8aa3b, v77
	v_exp_f32_e32 v75, v75
	v_pk_mul_f32 v[68:69], v[4:5], v[68:69]
	v_add_f32_e32 v75, 1.0, v75
	v_rcp_f32_e32 v79, v75
	v_pk_mul_f32 v[70:71], v[70:71], v[74:75] op_sel_hi:[1,0]
	v_pk_mul_f32 v[76:77], v[78:79], v[76:77]
	s_nop 0
	v_pk_mul_f32 v[68:69], v[76:77], v[68:69]
	v_lshlrev_b32_e32 v76, 16, v191
	v_cvt_pk_bf16_f32 v68, v68, v69
	v_mul_f32_e32 v69, 0xbfb8aa3b, v76
	v_exp_f32_e32 v69, v69
	v_and_b32_e32 v77, 0xffff0000, v191
	v_pk_mul_f32 v[70:71], v[6:7], v[70:71]
	v_add_f32_e32 v69, 1.0, v69
	v_rcp_f32_e32 v78, v69
	v_mul_f32_e32 v69, 0xbfb8aa3b, v77
	v_exp_f32_e32 v69, v69
	s_nop 0
	v_add_f32_e32 v69, 1.0, v69
	v_rcp_f32_e32 v79, v69
	s_nop 0
	v_pk_mul_f32 v[74:75], v[78:79], v[76:77]
	s_nop 0
	v_pk_mul_f32 v[70:71], v[74:75], v[70:71]
	s_nop 0
	v_cvt_pk_bf16_f32 v69, v70, v71
	global_store_dwordx2 v[72:73], v[68:69], off offset:96 sc0 sc1
	v_lshlrev_b32_e32 v68, 16, v186
	v_and_b32_e32 v69, 0xffff0000, v186
	v_lshlrev_b32_e32 v70, 16, v187
	v_and_b32_e32 v71, 0xffff0000, v187
	s_nop 1
	v_mfma_f32_16x16x32_bf16 v[68:71], v[56:59], v[64:67], v[68:71]
	v_mfma_f32_16x16x32_bf16 v[68:71], v[52:55], v[60:63], v[68:71]
	s_nop 7
	v_pk_mul_f32 v[72:73], v[70:71], v[70:71]
	v_pk_mul_f32 v[74:75], v[68:69], v[68:69]
	s_nop 0
	v_pk_mov_b32 v[76:77], v[74:75], v[72:73] op_sel:[1,0]
	v_mov_b32_e32 v75, v73
	v_pk_add_f32 v[84:85], v[76:77], v[74:75]
	v_lshlrev_b32_e32 v72, 16, v182
	v_and_b32_e32 v73, 0xffff0000, v182
	v_lshlrev_b32_e32 v74, 16, v183
	v_and_b32_e32 v75, 0xffff0000, v183
	s_nop 1
	v_mfma_f32_16x16x32_bf16 v[72:75], v[48:51], v[64:67], v[72:75]
	v_mfma_f32_16x16x32_bf16 v[72:75], v[44:47], v[60:63], v[72:75]
	s_nop 7
	v_pk_mul_f32 v[76:77], v[74:75], v[74:75]
	v_pk_mul_f32 v[78:79], v[72:73], v[72:73]
	s_nop 0
	v_pk_mov_b32 v[80:81], v[78:79], v[76:77] op_sel:[1,0]
	v_mov_b32_e32 v79, v77
	v_pk_add_f32 v[86:87], v[80:81], v[78:79]
	v_lshlrev_b32_e32 v76, 16, v178
	v_and_b32_e32 v77, 0xffff0000, v178
	v_lshlrev_b32_e32 v78, 16, v179
	v_and_b32_e32 v79, 0xffff0000, v179
	v_lshlrev_b32_e32 v80, 16, v176
	v_and_b32_e32 v81, 0xffff0000, v176
	v_mfma_f32_16x16x32_bf16 v[76:79], v[40:43], v[64:67], v[76:79]
	s_nop 0
	v_mfma_f32_16x16x32_bf16 v[64:67], v[32:35], v[64:67], v[80:83]
	v_mfma_f32_16x16x32_bf16 v[76:79], v[36:39], v[60:63], v[76:79]
	v_mfma_f32_16x16x32_bf16 v[60:63], v[28:31], v[60:63], v[64:67]
	s_nop 5
	v_add_f32_e64 v64, v84, v85
	v_add_f32_e64 v65, v85, v84
	v_mul_f32_e32 v66, v60, v60
	v_mul_f32_e32 v80, v61, v61
	v_mov_b32_e32 v65, v66
	v_pk_add_f32 v[66:67], v[86:87], v[86:87] op_sel:[0,1] op_sel_hi:[1,0]
	v_mul_f32_e32 v81, v62, v62
	v_mov_b32_e32 v67, v80
	v_pk_add_f32 v[64:65], v[64:65], v[66:67]
	v_mul_f32_e32 v66, v77, v77
	v_pk_fma_f32 v[66:67], v[76:77], v[76:77], v[66:67] op_sel_hi:[1,1,0]
	v_mul_f32_e32 v80, v79, v79
	v_mul_f32_e32 v82, v63, v63
	v_mov_b32_e32 v67, v81
	v_pk_fma_f32 v[80:81], v[78:79], v[78:79], v[80:81] op_sel_hi:[1,1,0]
	s_nop 0
	v_mov_b32_e32 v81, v82
	v_pk_add_f32 v[66:67], v[66:67], v[80:81]
	s_nop 0
	v_pk_add_f32 v[80:81], v[64:65], v[66:67]
	v_lshlrev_b32_e32 v66, 16, v180
	v_and_b32_e32 v67, 0xffff0000, v180
	v_mul_f32_e32 v82, 0xbfb8aa3b, v66
	v_mul_f32_e32 v83, 0xbfb8aa3b, v67
	v_exp_f32_e32 v82, v82
	v_exp_f32_e32 v83, v83
	v_lshlrev_b64 v[64:65], 11, v[184:185]
	v_lshl_add_u64 v[64:65], v[148:149], 0, v[64:65]
	v_add_f32_e32 v82, 1.0, v82
	v_add_f32_e32 v83, 1.0, v83
	v_rcp_f32_e32 v82, v82
	v_rcp_f32_e32 v83, v83
	s_nop 0
	v_pk_mul_f32 v[66:67], v[82:83], v[66:67]
	v_lshlrev_b32_e32 v82, 16, v181
	v_and_b32_e32 v83, 0xffff0000, v181
	v_mul_f32_e32 v84, 0xbfb8aa3b, v82
	v_mul_f32_e32 v85, 0xbfb8aa3b, v83
	v_exp_f32_e32 v84, v84
	v_exp_f32_e32 v85, v85
	v_add_f32_e32 v84, 1.0, v84
	v_add_f32_e32 v85, 1.0, v85
	v_rcp_f32_e32 v84, v84
	v_rcp_f32_e32 v85, v85
	s_nop 0
	v_pk_mul_f32 v[82:83], v[84:85], v[82:83]
	v_lshlrev_b32_e32 v84, 16, v174
	v_and_b32_e32 v85, 0xffff0000, v174
	v_mul_f32_e32 v86, 0xbfb8aa3b, v84
	v_mul_f32_e32 v87, 0xbfb8aa3b, v85
	v_exp_f32_e32 v86, v86
	v_exp_f32_e32 v87, v87
	v_add_f32_e32 v86, 1.0, v86
	v_add_f32_e32 v87, 1.0, v87
	v_rcp_f32_e32 v86, v86
	v_rcp_f32_e32 v87, v87
	s_nop 0
	v_pk_mul_f32 v[84:85], v[86:87], v[84:85]
	v_lshlrev_b32_e32 v86, 16, v175
	v_and_b32_e32 v87, 0xffff0000, v175
	v_mul_f32_e32 v88, 0xbfb8aa3b, v86
	v_mul_f32_e32 v89, 0xbfb8aa3b, v87
	v_exp_f32_e32 v88, v88
	v_exp_f32_e32 v89, v89
	v_add_f32_e32 v88, 1.0, v88
	v_add_f32_e32 v89, 1.0, v89
	v_rcp_f32_e32 v88, v88
	v_rcp_f32_e32 v89, v89
	s_nop 0
	v_pk_mul_f32 v[86:87], v[88:89], v[86:87]
	v_lshlrev_b32_e32 v88, 16, v172
	v_and_b32_e32 v89, 0xffff0000, v172
	v_mul_f32_e32 v90, 0xbfb8aa3b, v88
	v_mul_f32_e32 v91, 0xbfb8aa3b, v89
	v_exp_f32_e32 v90, v90
	v_exp_f32_e32 v91, v91
	v_add_f32_e32 v90, 1.0, v90
	v_add_f32_e32 v91, 1.0, v91
	v_rcp_f32_e32 v90, v90
	v_rcp_f32_e32 v91, v91
	s_nop 0
	v_pk_mul_f32 v[88:89], v[90:91], v[88:89]
	v_lshlrev_b32_e32 v90, 16, v173
	v_and_b32_e32 v91, 0xffff0000, v173
	v_mul_f32_e32 v92, 0xbfb8aa3b, v90
	v_mul_f32_e32 v93, 0xbfb8aa3b, v91
	v_exp_f32_e32 v92, v92
	v_exp_f32_e32 v93, v93
	v_add_f32_e32 v92, 1.0, v92
	v_add_f32_e32 v93, 1.0, v93
	v_rcp_f32_e32 v92, v92
	v_rcp_f32_e32 v93, v93
	s_nop 0
	v_pk_mul_f32 v[90:91], v[92:93], v[90:91]
	v_lshlrev_b32_e32 v92, 16, v170
	v_and_b32_e32 v93, 0xffff0000, v170
	v_mul_f32_e32 v94, 0xbfb8aa3b, v92
	v_mul_f32_e32 v95, 0xbfb8aa3b, v93
	v_exp_f32_e32 v94, v94
	v_exp_f32_e32 v95, v95
	v_add_f32_e32 v94, 1.0, v94
	v_add_f32_e32 v95, 1.0, v95
	v_rcp_f32_e32 v94, v94
	v_rcp_f32_e32 v95, v95
	s_nop 0
	v_pk_mul_f32 v[92:93], v[94:95], v[92:93]
	v_lshlrev_b32_e32 v94, 16, v171
	v_and_b32_e32 v95, 0xffff0000, v171
	v_mul_f32_e32 v96, 0xbfb8aa3b, v94
	v_mul_f32_e32 v97, 0xbfb8aa3b, v95
	v_exp_f32_e32 v96, v96
	v_exp_f32_e32 v97, v97
	v_add_f32_e32 v96, 1.0, v96
	v_add_f32_e32 v97, 1.0, v97
	v_rcp_f32_e32 v96, v96
	v_rcp_f32_e32 v97, v97
	s_nop 0
	v_pk_mul_f32 v[94:95], v[96:97], v[94:95]
	v_lshlrev_b32_e32 v96, 16, v168
	v_and_b32_e32 v97, 0xffff0000, v168
	s_nop 1
	v_mfma_f32_16x16x32_bf16 v[56:59], v[56:59], v[24:27], v[96:99]
	v_mfma_f32_16x16x32_bf16 v[52:55], v[52:55], v[20:23], v[56:59]
	s_nop 7
	v_pk_mul_f32 v[56:57], v[54:55], v[54:55]
	v_pk_mul_f32 v[58:59], v[52:53], v[52:53]
	s_nop 0
	v_pk_mov_b32 v[96:97], v[58:59], v[56:57] op_sel:[1,0]
	v_mov_b32_e32 v59, v57
	v_pk_add_f32 v[96:97], v[96:97], v[58:59]
	v_lshlrev_b32_e32 v56, 16, v154
	v_and_b32_e32 v57, 0xffff0000, v154
	v_lshlrev_b32_e32 v58, 16, v155
	v_and_b32_e32 v59, 0xffff0000, v155
	s_nop 1
	v_mfma_f32_16x16x32_bf16 v[48:51], v[48:51], v[24:27], v[56:59]
	v_mfma_f32_16x16x32_bf16 v[44:47], v[44:47], v[20:23], v[48:51]
	s_nop 7
	v_pk_mul_f32 v[48:49], v[46:47], v[46:47]
	v_pk_mul_f32 v[50:51], v[44:45], v[44:45]
	s_nop 0
	v_pk_mov_b32 v[56:57], v[50:51], v[48:49] op_sel:[1,0]
	v_mov_b32_e32 v51, v49
	v_pk_add_f32 v[56:57], v[56:57], v[50:51]
	v_lshlrev_b32_e32 v48, 16, v152
	v_and_b32_e32 v49, 0xffff0000, v152
	v_lshlrev_b32_e32 v50, 16, v153
	v_and_b32_e32 v51, 0xffff0000, v153
	s_nop 1
	v_mfma_f32_16x16x32_bf16 v[40:43], v[40:43], v[24:27], v[48:51]
	v_mfma_f32_16x16x32_bf16 v[36:39], v[36:39], v[20:23], v[40:43]
	s_nop 6
	v_lshlrev_b32_e32 v40, 16, v150
	v_and_b32_e32 v41, 0xffff0000, v150
	v_lshlrev_b32_e32 v42, 16, v151
	v_and_b32_e32 v43, 0xffff0000, v151
	s_nop 1
	v_mfma_f32_16x16x32_bf16 v[24:27], v[32:35], v[24:27], v[40:43]
	v_mfma_f32_16x16x32_bf16 v[20:23], v[28:31], v[20:23], v[24:27]
	s_nop 6
	v_add_f32_e64 v24, v96, v97
	v_add_f32_e64 v25, v97, v96
	v_mul_f32_e32 v26, v20, v20
	v_mul_f32_e32 v28, v21, v21
	v_mov_b32_e32 v25, v26
	v_pk_add_f32 v[26:27], v[56:57], v[56:57] op_sel:[0,1] op_sel_hi:[1,0]
	v_mul_f32_e32 v29, v22, v22
	v_mov_b32_e32 v27, v28
	v_pk_add_f32 v[24:25], v[24:25], v[26:27]
	v_mul_f32_e32 v26, v37, v37
	v_pk_fma_f32 v[26:27], v[36:37], v[36:37], v[26:27] op_sel_hi:[1,1,0]
	v_mul_f32_e32 v28, v39, v39
	v_mul_f32_e32 v30, v23, v23
	v_mov_b32_e32 v27, v29
	v_pk_fma_f32 v[28:29], v[38:39], v[38:39], v[28:29] op_sel_hi:[1,1,0]
	s_nop 0
	v_mov_b32_e32 v29, v30
	v_pk_add_f32 v[26:27], v[26:27], v[28:29]
	s_nop 0
	v_pk_add_f32 v[24:25], v[24:25], v[26:27]
	v_mov_b32_e32 v27, v80
	v_mov_b32_e32 v26, v24
	v_mov_b32_e32 v80, v25
	v_pk_add_f32 v[24:25], v[26:27], v[80:81]
	ds_bpermute_b32 v27, v131, v25
	ds_bpermute_b32 v26, v131, v24
	s_waitcnt lgkmcnt(0)
	v_pk_add_f32 v[24:25], v[24:25], v[26:27]
	ds_bpermute_b32 v27, v129, v25
	ds_bpermute_b32 v26, v129, v24
	s_waitcnt lgkmcnt(0)
	v_pk_add_f32 v[24:25], v[24:25], v[26:27]
	s_nop 0
	v_pk_fma_f32 v[24:25], v[24:25], s[84:85], v[188:189] op_sel_hi:[1,0,0]
	s_nop 0
	v_mul_f32_e32 v26, 0x4b800000, v25
	v_cmp_gt_f32_e64 s[4:5], s75, v25
	v_cmp_gt_f32_e32 vcc, s75, v24
	s_nop 0
	v_cndmask_b32_e64 v25, v25, v26, s[4:5]
	v_rsq_f32_e32 v25, v25
	s_nop 0
	v_mul_f32_e32 v26, 0x45800000, v25
	v_cndmask_b32_e64 v26, v25, v26, s[4:5]
	v_pk_mul_f32 v[28:29], v[68:69], v[26:27] op_sel_hi:[1,0]
	v_pk_mul_f32 v[30:31], v[70:71], v[26:27] op_sel_hi:[1,0]
	v_pk_mul_f32 v[28:29], v[16:17], v[28:29]
	v_pk_mul_f32 v[30:31], v[18:19], v[30:31]
	v_pk_mul_f32 v[28:29], v[66:67], v[28:29]
	v_pk_mul_f32 v[30:31], v[82:83], v[30:31]
	v_cvt_pk_bf16_f32 v28, v28, v29
	v_cvt_pk_bf16_f32 v29, v30, v31
	global_store_dwordx2 v[64:65], v[28:29], off sc0 sc1
	v_pk_mul_f32 v[28:29], v[72:73], v[26:27] op_sel_hi:[1,0]
	v_pk_mul_f32 v[30:31], v[74:75], v[26:27] op_sel_hi:[1,0]
	v_pk_mul_f32 v[28:29], v[12:13], v[28:29]
	v_pk_mul_f32 v[30:31], v[14:15], v[30:31]
	v_pk_mul_f32 v[28:29], v[84:85], v[28:29]
	v_pk_mul_f32 v[30:31], v[86:87], v[30:31]
	v_cvt_pk_bf16_f32 v28, v28, v29
	v_cvt_pk_bf16_f32 v29, v30, v31
	global_store_dwordx2 v[64:65], v[28:29], off offset:32 sc0 sc1
	v_pk_mul_f32 v[28:29], v[76:77], v[26:27] op_sel_hi:[1,0]
	v_pk_mul_f32 v[30:31], v[78:79], v[26:27] op_sel_hi:[1,0]
	v_pk_mul_f32 v[28:29], v[8:9], v[28:29]
	v_pk_mul_f32 v[30:31], v[10:11], v[30:31]
	v_pk_mul_f32 v[28:29], v[88:89], v[28:29]
	v_pk_mul_f32 v[30:31], v[90:91], v[30:31]
	v_cvt_pk_bf16_f32 v28, v28, v29
	v_cvt_pk_bf16_f32 v29, v30, v31
	global_store_dwordx2 v[64:65], v[28:29], off offset:64 sc0 sc1
	v_pk_mul_f32 v[28:29], v[60:61], v[26:27] op_sel_hi:[1,0]
	v_pk_mul_f32 v[26:27], v[62:63], v[26:27] op_sel_hi:[1,0]
	v_pk_mul_f32 v[28:29], v[4:5], v[28:29]
	v_pk_mul_f32 v[26:27], v[6:7], v[26:27]
	v_pk_mul_f32 v[28:29], v[92:93], v[28:29]
	v_pk_mul_f32 v[26:27], v[94:95], v[26:27]
	v_cvt_pk_bf16_f32 v28, v28, v29
	v_cvt_pk_bf16_f32 v29, v26, v27
	v_mul_f32_e32 v25, 0x4b800000, v24
	global_store_dwordx2 v[64:65], v[28:29], off offset:96 sc0 sc1
	v_cndmask_b32_e32 v24, v24, v25, vcc
	v_lshlrev_b32_e32 v28, 16, v144
	v_rsq_f32_e32 v24, v24
	v_mul_f32_e32 v27, 0xbfb8aa3b, v28
	v_exp_f32_e32 v27, v27
	v_and_b32_e32 v29, 0xffff0000, v144
	v_mul_f32_e32 v25, 0x45800000, v24
	v_cndmask_b32_e32 v26, v24, v25, vcc
	v_add_f32_e32 v27, 1.0, v27
	v_rcp_f32_e32 v30, v27
	v_pk_mul_f32 v[32:33], v[52:53], v[26:27] op_sel_hi:[1,0]
	v_mul_f32_e32 v27, 0xbfb8aa3b, v29
	v_exp_f32_e32 v27, v27
	v_pk_mul_f32 v[16:17], v[16:17], v[32:33]
	v_lshlrev_b64 v[24:25], 11, v[146:147]
	v_lshl_add_u64 v[24:25], v[148:149], 0, v[24:25]
	v_add_f32_e32 v27, 1.0, v27
	v_rcp_f32_e32 v31, v27
	v_pk_mul_f32 v[32:33], v[54:55], v[26:27] op_sel_hi:[1,0]
	s_mov_b64 s[4:5], 0
	v_pk_mul_f32 v[18:19], v[18:19], v[32:33]
	v_pk_mul_f32 v[28:29], v[30:31], v[28:29]
	s_nop 0
	v_pk_mul_f32 v[16:17], v[28:29], v[16:17]
	v_lshlrev_b32_e32 v28, 16, v145
	v_cvt_pk_bf16_f32 v16, v16, v17
	v_mul_f32_e32 v17, 0xbfb8aa3b, v28
	v_exp_f32_e32 v17, v17
	v_and_b32_e32 v29, 0xffff0000, v145
	v_add_f32_e32 v17, 1.0, v17
	v_rcp_f32_e32 v30, v17
	v_mul_f32_e32 v17, 0xbfb8aa3b, v29
	v_exp_f32_e32 v17, v17
	s_nop 0
	v_add_f32_e32 v17, 1.0, v17
	v_rcp_f32_e32 v31, v17
	s_nop 0
	v_pk_mul_f32 v[28:29], v[30:31], v[28:29]
	s_nop 0
	v_pk_mul_f32 v[18:19], v[28:29], v[18:19]
	v_pk_mul_f32 v[28:29], v[44:45], v[26:27] op_sel_hi:[1,0]
	v_cvt_pk_bf16_f32 v17, v18, v19
	global_store_dwordx2 v[24:25], v[16:17], off sc0 sc1
	v_lshlrev_b32_e32 v16, 16, v142
	v_and_b32_e32 v17, 0xffff0000, v142
	v_mul_f32_e32 v18, 0xbfb8aa3b, v16
	v_mul_f32_e32 v19, 0xbfb8aa3b, v17
	v_exp_f32_e32 v18, v18
	v_exp_f32_e32 v19, v19
	v_pk_mul_f32 v[12:13], v[12:13], v[28:29]
	v_pk_mul_f32 v[28:29], v[46:47], v[26:27] op_sel_hi:[1,0]
	v_add_f32_e32 v18, 1.0, v18
	v_add_f32_e32 v19, 1.0, v19
	v_rcp_f32_e32 v18, v18
	v_rcp_f32_e32 v19, v19
	v_pk_mul_f32 v[14:15], v[14:15], v[28:29]
	v_pk_mul_f32 v[16:17], v[18:19], v[16:17]
	s_nop 0
	v_pk_mul_f32 v[12:13], v[16:17], v[12:13]
	v_lshlrev_b32_e32 v16, 16, v143
	v_cvt_pk_bf16_f32 v12, v12, v13
	v_mul_f32_e32 v13, 0xbfb8aa3b, v16
	v_exp_f32_e32 v13, v13
	v_and_b32_e32 v17, 0xffff0000, v143
	v_add_f32_e32 v13, 1.0, v13
	v_rcp_f32_e32 v18, v13
	v_mul_f32_e32 v13, 0xbfb8aa3b, v17
	v_exp_f32_e32 v13, v13
	s_nop 0
	v_add_f32_e32 v13, 1.0, v13
	v_rcp_f32_e32 v19, v13
	s_nop 0
	v_pk_mul_f32 v[16:17], v[18:19], v[16:17]
	s_nop 0
	v_pk_mul_f32 v[14:15], v[16:17], v[14:15]
	v_pk_mul_f32 v[16:17], v[36:37], v[26:27] op_sel_hi:[1,0]
	v_cvt_pk_bf16_f32 v13, v14, v15
	global_store_dwordx2 v[24:25], v[12:13], off offset:32 sc0 sc1
	v_lshlrev_b32_e32 v12, 16, v140
	v_and_b32_e32 v13, 0xffff0000, v140
	v_mul_f32_e32 v14, 0xbfb8aa3b, v12
	v_mul_f32_e32 v15, 0xbfb8aa3b, v13
	v_exp_f32_e32 v14, v14
	v_exp_f32_e32 v15, v15
	v_pk_mul_f32 v[8:9], v[8:9], v[16:17]
	v_pk_mul_f32 v[16:17], v[38:39], v[26:27] op_sel_hi:[1,0]
	v_add_f32_e32 v14, 1.0, v14
	v_add_f32_e32 v15, 1.0, v15
	v_rcp_f32_e32 v14, v14
	v_rcp_f32_e32 v15, v15
	v_pk_mul_f32 v[10:11], v[10:11], v[16:17]
	v_pk_mul_f32 v[12:13], v[14:15], v[12:13]
	s_nop 0
	v_pk_mul_f32 v[8:9], v[12:13], v[8:9]
	v_lshlrev_b32_e32 v12, 16, v141
	v_cvt_pk_bf16_f32 v8, v8, v9
	v_mul_f32_e32 v9, 0xbfb8aa3b, v12
	v_exp_f32_e32 v9, v9
	v_and_b32_e32 v13, 0xffff0000, v141
	v_add_f32_e32 v9, 1.0, v9
	v_rcp_f32_e32 v14, v9
	v_mul_f32_e32 v9, 0xbfb8aa3b, v13
	v_exp_f32_e32 v9, v9
	s_nop 0
	v_add_f32_e32 v9, 1.0, v9
	v_rcp_f32_e32 v15, v9
	s_nop 0
	v_pk_mul_f32 v[12:13], v[14:15], v[12:13]
	s_nop 0
	v_pk_mul_f32 v[10:11], v[12:13], v[10:11]
	v_pk_mul_f32 v[12:13], v[20:21], v[26:27] op_sel_hi:[1,0]
	v_cvt_pk_bf16_f32 v9, v10, v11
	global_store_dwordx2 v[24:25], v[8:9], off offset:64 sc0 sc1
	v_lshlrev_b32_e32 v8, 16, v138
	v_and_b32_e32 v9, 0xffff0000, v138
	v_mul_f32_e32 v10, 0xbfb8aa3b, v8
	v_mul_f32_e32 v11, 0xbfb8aa3b, v9
	v_exp_f32_e32 v10, v10
	v_exp_f32_e32 v11, v11
	v_pk_mul_f32 v[4:5], v[4:5], v[12:13]
	v_pk_mul_f32 v[12:13], v[22:23], v[26:27] op_sel_hi:[1,0]
	v_add_f32_e32 v10, 1.0, v10
	v_add_f32_e32 v11, 1.0, v11
	v_rcp_f32_e32 v10, v10
	v_rcp_f32_e32 v11, v11
	v_pk_mul_f32 v[6:7], v[6:7], v[12:13]
	v_pk_mul_f32 v[8:9], v[10:11], v[8:9]
	s_nop 0
	v_pk_mul_f32 v[4:5], v[8:9], v[4:5]
	v_lshlrev_b32_e32 v8, 16, v139
	v_cvt_pk_bf16_f32 v4, v4, v5
	v_mul_f32_e32 v5, 0xbfb8aa3b, v8
	v_exp_f32_e32 v5, v5
	v_and_b32_e32 v9, 0xffff0000, v139
	v_add_f32_e32 v5, 1.0, v5
	v_rcp_f32_e32 v10, v5
	v_mul_f32_e32 v5, 0xbfb8aa3b, v9
	v_exp_f32_e32 v5, v5
	s_nop 0
	v_add_f32_e32 v5, 1.0, v5
	v_rcp_f32_e32 v11, v5
	s_nop 0
	v_pk_mul_f32 v[8:9], v[10:11], v[8:9]
	s_nop 0
	v_pk_mul_f32 v[6:7], v[8:9], v[6:7]
	s_nop 0
	v_cvt_pk_bf16_f32 v5, v6, v7
	global_store_dwordx2 v[24:25], v[4:5], off offset:96 sc0 sc1
.LBB0_1014:
	s_andn2_b64 vcc, exec, s[4:5]
	s_cbranch_vccnz .LBB0_952
	s_ashr_i32 s21, s20, 31
	s_add_u32 s27, s38, s27
	s_addc_u32 s26, s39, s26
	s_lshl_b64 s[4:5], s[20:21], 22
	s_add_u32 s20, s0, s4
	s_addc_u32 s21, s1, s5
	s_ashr_i32 s25, s24, 31
	s_lshl_b32 s4, s55, 6
	s_lshl_b64 s[6:7], s[24:25], 13
	s_ashr_i32 s23, s22, 31
	s_lshl_b64 s[24:25], s[24:25], 18
	s_add_u32 s5, s48, s24
	s_addc_u32 s24, s49, s25
	s_lshl_b64 s[22:23], s[22:23], 14
	s_add_u32 s22, s5, s22
	s_addc_u32 s23, s24, s23
	v_mov_b32_e32 v137, v3
	v_lshl_add_u64 v[4:5], s[22:23], 0, v[2:3]
	v_lshl_add_u64 v[6:7], v[4:5], 0, v[136:137]
	s_mov_b64 s[22:23], 0x2000
	v_add_co_u32_e32 v10, vcc, s63, v6
	v_lshl_add_u64 v[8:9], v[6:7], 0, s[22:23]
	s_nop 0
	v_addc_co_u32_e32 v11, vcc, 0, v7, vcc
	s_mov_b64 s[22:23], 0x6000
	global_load_dwordx4 v[76:79], v[10:11], off
	global_load_dwordx4 v[72:75], v[8:9], off offset:64
	v_mov_b32_e32 v105, v3
	v_lshl_add_u64 v[8:9], v[6:7], 0, s[22:23]
	v_add_co_u32_e32 v6, vcc, s57, v6
	v_lshl_add_u64 v[4:5], v[4:5], 0, v[104:105]
	s_nop 0
	v_addc_co_u32_e32 v7, vcc, 0, v7, vcc
	global_load_dwordx2 v[44:45], v[4:5], off
	global_load_dwordx2 v[56:57], v[4:5], off offset:32
	global_load_dwordx2 v[68:69], v[4:5], off offset:64
	global_load_dwordx2 v[100:101], v[4:5], off offset:96
	global_load_dwordx4 v[24:27], v[6:7], off
	global_load_dwordx4 v[20:23], v[8:9], off offset:64
	v_lshl_add_u64 v[6:7], v[4:5], 0, s[50:51]
	v_add_co_u32_e32 v4, vcc, s65, v4
	s_mov_b32 s5, 0x41000
	s_nop 0
	v_addc_co_u32_e32 v5, vcc, 0, v5, vcc
	global_load_dwordx2 v[98:99], v[4:5], off
	global_load_dwordx2 v[96:97], v[6:7], off offset:32
	global_load_dwordx2 v[92:93], v[6:7], off offset:64
	global_load_dwordx2 v[88:89], v[6:7], off offset:96
	v_lshl_add_u64 v[4:5], v[118:119], 0, s[6:7]
	s_mov_b64 s[6:7], 0x40000
	v_lshl_add_u64 v[6:7], v[4:5], 0, s[6:7]
	v_add_co_u32_e32 v4, vcc, s5, v4
	s_ashr_i32 s5, s4, 31
	s_nop 0
	v_addc_co_u32_e32 v5, vcc, 0, v5, vcc
	global_load_dwordx4 v[60:63], v[4:5], off offset:-4096
	global_load_dwordx4 v[64:67], v[6:7], off offset:64
	global_load_dwordx4 v[52:55], v[6:7], off offset:2048
	global_load_dwordx4 v[48:51], v[6:7], off offset:2112
	global_load_dwordx4 v[40:43], v[4:5], off
	global_load_dwordx4 v[36:39], v[4:5], off offset:64
	global_load_dwordx4 v[32:35], v[4:5], off offset:2048
	global_load_dwordx4 v[28:31], v[4:5], off offset:2112
	s_lshl_b64 s[4:5], s[4:5], 1
	s_add_u32 s6, s27, s4
	s_addc_u32 s7, s26, s5
	v_lshl_add_u64 v[4:5], s[6:7], 0, v[104:105]
	s_mov_b64 s[6:7], 0x1a00
	s_lshl_b32 s22, s54, 6
	v_lshl_add_u64 v[4:5], v[4:5], 0, s[6:7]
	v_or_b32_e32 v146, s22, v0
	v_mad_i64_i32 v[6:7], s[6:7], v146, s64, v[4:5]
	global_load_dwordx2 v[102:103], v[6:7], off
	global_load_dwordx2 v[138:139], v[6:7], off offset:32
	global_load_dwordx2 v[140:141], v[6:7], off offset:64
	global_load_dwordx2 v[136:137], v[6:7], off offset:96
	v_and_b32_e32 v46, 64, v234
	v_xor_b32_e32 v2, 16, v234
	v_add_u32_e32 v46, 64, v46
	v_cmp_lt_i32_e32 vcc, v2, v46
	s_add_u32 s4, s20, s4
	s_addc_u32 s5, s21, s5
	v_cndmask_b32_e32 v2, v234, v2, vcc
	v_lshlrev_b32_e32 v129, 2, v2
	v_xor_b32_e32 v2, 32, v234
	v_cmp_lt_i32_e32 vcc, v2, v46
	v_lshl_add_u64 v[94:95], s[4:5], 0, v[104:105]
	v_ashrrev_i32_e32 v147, 31, v146
	v_add_u32_e32 v90, s22, v1
	v_mad_i64_i32 v[4:5], s[6:7], v90, s64, v[4:5]
	global_load_dwordx2 v[86:87], v[4:5], off
	global_load_dwordx2 v[84:85], v[4:5], off offset:32
	global_load_dwordx2 v[82:83], v[4:5], off offset:64
	global_load_dwordx2 v[80:81], v[4:5], off offset:96
	global_load_dwordx4 v[16:19], v[122:123], off
	global_load_dwordx4 v[12:15], v[122:123], off offset:64
	global_load_dwordx4 v[8:11], v[122:123], off offset:128
	s_nop 0
	global_load_dwordx4 v[4:7], v[122:123], off offset:192
	v_cndmask_b32_e32 v2, v234, v2, vcc
	v_lshlrev_b32_e32 v2, 2, v2
	v_ashrrev_i32_e32 v91, 31, v90
	s_waitcnt vmcnt(29)
	v_lshlrev_b32_e32 v142, 16, v44
	v_and_b32_e32 v143, 0xffff0000, v44
	v_lshlrev_b32_e32 v144, 16, v45
	v_and_b32_e32 v145, 0xffff0000, v45
	s_waitcnt vmcnt(19)
	s_nop 0
	v_mfma_f32_16x16x32_bf16 v[44:47], v[60:63], v[76:79], v[142:145]
	s_nop 2
	v_lshlrev_b32_e32 v142, 16, v56
	v_and_b32_e32 v143, 0xffff0000, v56
	v_lshlrev_b32_e32 v144, 16, v57
	s_waitcnt vmcnt(18)
	v_mfma_f32_16x16x32_bf16 v[44:47], v[64:67], v[72:75], v[44:47]
	v_and_b32_e32 v145, 0xffff0000, v57
	s_nop 6
	v_pk_mul_f32 v[58:59], v[46:47], v[46:47]
	v_pk_mul_f32 v[70:71], v[44:45], v[44:45]
	s_nop 0
	v_pk_mov_b32 v[104:105], v[70:71], v[58:59] op_sel:[1,0]
	v_mov_b32_e32 v71, v59
	s_waitcnt vmcnt(17)
	v_mfma_f32_16x16x32_bf16 v[56:59], v[52:55], v[76:79], v[142:145]
	v_add_f32_e64 v104, v104, v70
	v_add_f32_e64 v105, v105, v71
	s_waitcnt vmcnt(16)
	v_mfma_f32_16x16x32_bf16 v[56:59], v[48:51], v[72:75], v[56:59]
	s_nop 7
	v_pk_mul_f32 v[70:71], v[58:59], v[58:59]
	v_pk_mul_f32 v[142:143], v[56:57], v[56:57]
	s_nop 0
	v_pk_mov_b32 v[144:145], v[142:143], v[70:71] op_sel:[1,0]
	v_mov_b32_e32 v143, v71
	v_pk_add_f32 v[148:149], v[144:145], v[142:143]
	v_lshlrev_b32_e32 v142, 16, v68
	v_and_b32_e32 v143, 0xffff0000, v68
	v_lshlrev_b32_e32 v144, 16, v69
	v_and_b32_e32 v145, 0xffff0000, v69
	s_waitcnt vmcnt(15)
	s_nop 0
	v_mfma_f32_16x16x32_bf16 v[68:71], v[40:43], v[76:79], v[142:145]
	s_nop 2
	v_lshlrev_b32_e32 v142, 16, v100
	v_and_b32_e32 v143, 0xffff0000, v100
	v_lshlrev_b32_e32 v144, 16, v101
	v_and_b32_e32 v145, 0xffff0000, v101
	s_waitcnt vmcnt(14)
	v_mfma_f32_16x16x32_bf16 v[68:71], v[36:39], v[72:75], v[68:71]
	s_waitcnt vmcnt(13)
	v_mfma_f32_16x16x32_bf16 v[76:79], v[32:35], v[76:79], v[142:145]
	s_waitcnt vmcnt(12)
	v_mfma_f32_16x16x32_bf16 v[72:75], v[28:31], v[72:75], v[76:79]
	s_nop 5
	v_add_f32_e64 v76, v104, v105
	v_add_f32_e64 v77, v105, v104
	v_mul_f32_e32 v78, v72, v72
	v_mul_f32_e32 v100, v73, v73
	v_mov_b32_e32 v77, v78
	v_pk_add_f32 v[78:79], v[148:149], v[148:149] op_sel:[0,1] op_sel_hi:[1,0]
	v_mul_f32_e32 v101, v74, v74
	v_mov_b32_e32 v79, v100
	v_pk_add_f32 v[76:77], v[76:77], v[78:79]
	v_mul_f32_e32 v78, v69, v69
	v_pk_fma_f32 v[78:79], v[68:69], v[68:69], v[78:79] op_sel_hi:[1,1,0]
	v_mul_f32_e32 v100, v71, v71
	v_mul_f32_e32 v131, v75, v75
	v_mov_b32_e32 v79, v101
	v_pk_fma_f32 v[100:101], v[70:71], v[70:71], v[100:101] op_sel_hi:[1,1,0]
	v_lshlrev_b32_e32 v148, 16, v99
	v_mov_b32_e32 v101, v131
	v_pk_add_f32 v[78:79], v[78:79], v[100:101]
	v_and_b32_e32 v149, 0xffff0000, v99
	v_pk_add_f32 v[100:101], v[76:77], v[78:79]
	s_waitcnt vmcnt(11)
	v_lshlrev_b32_e32 v78, 16, v102
	v_and_b32_e32 v79, 0xffff0000, v102
	v_mul_f32_e32 v102, 0xbfb8aa3b, v78
	v_exp_f32_e32 v102, v102
	v_lshlrev_b64 v[76:77], 11, v[146:147]
	v_lshl_add_u64 v[76:77], v[94:95], 0, v[76:77]
	v_add_f32_e32 v102, 1.0, v102
	v_rcp_f32_e32 v104, v102
	v_mul_f32_e32 v102, 0xbfb8aa3b, v79
	v_exp_f32_e32 v102, v102
	s_nop 0
	v_add_f32_e32 v102, 1.0, v102
	v_rcp_f32_e32 v105, v102
	v_lshlrev_b32_e32 v102, 16, v103
	v_and_b32_e32 v103, 0xffff0000, v103
	v_pk_mul_f32 v[78:79], v[104:105], v[78:79]
	v_mul_f32_e32 v104, 0xbfb8aa3b, v102
	v_mul_f32_e32 v105, 0xbfb8aa3b, v103
	v_exp_f32_e32 v104, v104
	v_exp_f32_e32 v105, v105
	v_add_f32_e32 v104, 1.0, v104
	v_add_f32_e32 v105, 1.0, v105
	v_rcp_f32_e32 v104, v104
	v_rcp_f32_e32 v105, v105
	s_nop 0
	v_pk_mul_f32 v[102:103], v[104:105], v[102:103]
	s_waitcnt vmcnt(10)
	v_lshlrev_b32_e32 v104, 16, v138
	v_mul_f32_e32 v131, 0xbfb8aa3b, v104
	v_exp_f32_e32 v131, v131
	v_and_b32_e32 v105, 0xffff0000, v138
	v_lshlrev_b32_e32 v138, 16, v139
	v_and_b32_e32 v139, 0xffff0000, v139
	v_add_f32_e32 v131, 1.0, v131
	v_rcp_f32_e32 v142, v131
	v_mul_f32_e32 v131, 0xbfb8aa3b, v105
	v_exp_f32_e32 v131, v131
	s_nop 0
	v_add_f32_e32 v131, 1.0, v131
	v_rcp_f32_e32 v143, v131
	v_mul_f32_e32 v131, 0xbfb8aa3b, v138
	v_exp_f32_e32 v131, v131
	v_pk_mul_f32 v[104:105], v[142:143], v[104:105]
	v_add_f32_e32 v131, 1.0, v131
	v_rcp_f32_e32 v142, v131
	v_mul_f32_e32 v131, 0xbfb8aa3b, v139
	v_exp_f32_e32 v131, v131
	s_nop 0
	v_add_f32_e32 v131, 1.0, v131
	v_rcp_f32_e32 v143, v131
	s_nop 0
	v_pk_mul_f32 v[138:139], v[142:143], v[138:139]
	s_waitcnt vmcnt(9)
	v_lshlrev_b32_e32 v142, 16, v140
	v_mul_f32_e32 v131, 0xbfb8aa3b, v142
	v_exp_f32_e32 v131, v131
	v_and_b32_e32 v143, 0xffff0000, v140
	v_lshlrev_b32_e32 v140, 16, v141
	v_and_b32_e32 v141, 0xffff0000, v141
	v_add_f32_e32 v131, 1.0, v131
	v_rcp_f32_e32 v144, v131
	v_mul_f32_e32 v131, 0xbfb8aa3b, v143
	v_exp_f32_e32 v131, v131
	s_nop 0
	v_add_f32_e32 v131, 1.0, v131
	v_rcp_f32_e32 v145, v131
	v_mul_f32_e32 v131, 0xbfb8aa3b, v140
	v_exp_f32_e32 v131, v131
	v_pk_mul_f32 v[142:143], v[144:145], v[142:143]
	v_add_f32_e32 v131, 1.0, v131
	v_rcp_f32_e32 v144, v131
	v_mul_f32_e32 v131, 0xbfb8aa3b, v141
	v_exp_f32_e32 v131, v131
	s_nop 0
	v_add_f32_e32 v131, 1.0, v131
	v_rcp_f32_e32 v145, v131
	s_nop 0
	v_pk_mul_f32 v[140:141], v[144:145], v[140:141]
	s_waitcnt vmcnt(8)
	v_lshlrev_b32_e32 v144, 16, v136
	v_mul_f32_e32 v131, 0xbfb8aa3b, v144
	v_exp_f32_e32 v131, v131
	v_and_b32_e32 v145, 0xffff0000, v136
	v_lshlrev_b32_e32 v136, 16, v137
	v_and_b32_e32 v137, 0xffff0000, v137
	v_add_f32_e32 v131, 1.0, v131
	v_rcp_f32_e32 v146, v131
	v_mul_f32_e32 v131, 0xbfb8aa3b, v145
	v_exp_f32_e32 v131, v131
	s_nop 0
	v_add_f32_e32 v131, 1.0, v131
	v_rcp_f32_e32 v147, v131
	v_mul_f32_e32 v131, 0xbfb8aa3b, v136
	v_exp_f32_e32 v131, v131
	v_pk_mul_f32 v[144:145], v[146:147], v[144:145]
	v_add_f32_e32 v131, 1.0, v131
	v_rcp_f32_e32 v146, v131
	v_mul_f32_e32 v131, 0xbfb8aa3b, v137
	v_exp_f32_e32 v131, v131
	s_nop 0
	v_add_f32_e32 v131, 1.0, v131
	v_rcp_f32_e32 v147, v131
	s_nop 0
	v_pk_mul_f32 v[136:137], v[146:147], v[136:137]
	v_lshlrev_b32_e32 v146, 16, v98
	v_and_b32_e32 v147, 0xffff0000, v98
	s_nop 1
	v_mfma_f32_16x16x32_bf16 v[60:63], v[60:63], v[24:27], v[146:149]
	v_mfma_f32_16x16x32_bf16 v[60:63], v[64:67], v[20:23], v[60:63]
	s_nop 7
	v_pk_mul_f32 v[64:65], v[62:63], v[62:63]
	v_pk_mul_f32 v[66:67], v[60:61], v[60:61]
	s_nop 0
	v_pk_mov_b32 v[98:99], v[66:67], v[64:65] op_sel:[1,0]
	v_mov_b32_e32 v67, v65
	v_pk_add_f32 v[98:99], v[98:99], v[66:67]
	v_lshlrev_b32_e32 v64, 16, v96
	v_and_b32_e32 v65, 0xffff0000, v96
	v_lshlrev_b32_e32 v66, 16, v97
	v_and_b32_e32 v67, 0xffff0000, v97
	s_nop 1
	v_mfma_f32_16x16x32_bf16 v[52:55], v[52:55], v[24:27], v[64:67]
	v_mfma_f32_16x16x32_bf16 v[48:51], v[48:51], v[20:23], v[52:55]
	s_nop 7
	v_pk_mul_f32 v[52:53], v[50:51], v[50:51]
	v_pk_mul_f32 v[54:55], v[48:49], v[48:49]
	s_nop 0
	v_pk_mov_b32 v[64:65], v[54:55], v[52:53] op_sel:[1,0]
	v_mov_b32_e32 v55, v53
	v_pk_add_f32 v[64:65], v[64:65], v[54:55]
	v_lshlrev_b32_e32 v52, 16, v92
	v_and_b32_e32 v53, 0xffff0000, v92
	v_lshlrev_b32_e32 v54, 16, v93
	v_and_b32_e32 v55, 0xffff0000, v93
	s_nop 1
	v_mfma_f32_16x16x32_bf16 v[40:43], v[40:43], v[24:27], v[52:55]
	v_mfma_f32_16x16x32_bf16 v[36:39], v[36:39], v[20:23], v[40:43]
	s_nop 6
	v_lshlrev_b32_e32 v40, 16, v88
	v_and_b32_e32 v41, 0xffff0000, v88
	v_lshlrev_b32_e32 v42, 16, v89
	v_and_b32_e32 v43, 0xffff0000, v89
	s_nop 1
	v_mfma_f32_16x16x32_bf16 v[24:27], v[32:35], v[24:27], v[40:43]
	v_mfma_f32_16x16x32_bf16 v[20:23], v[28:31], v[20:23], v[24:27]
	s_nop 6
	v_add_f32_e64 v24, v98, v99
	v_add_f32_e64 v25, v99, v98
	v_mul_f32_e32 v26, v20, v20
	v_mul_f32_e32 v28, v21, v21
	v_mov_b32_e32 v25, v26
	v_pk_add_f32 v[26:27], v[64:65], v[64:65] op_sel:[0,1] op_sel_hi:[1,0]
	v_mul_f32_e32 v29, v22, v22
	v_mov_b32_e32 v27, v28
	v_pk_add_f32 v[24:25], v[24:25], v[26:27]
	v_mul_f32_e32 v26, v37, v37
	v_pk_fma_f32 v[26:27], v[36:37], v[36:37], v[26:27] op_sel_hi:[1,1,0]
	v_mul_f32_e32 v28, v39, v39
	v_mul_f32_e32 v30, v23, v23
	v_mov_b32_e32 v27, v29
	v_pk_fma_f32 v[28:29], v[38:39], v[38:39], v[28:29] op_sel_hi:[1,1,0]
	s_nop 0
	v_mov_b32_e32 v29, v30
	v_pk_add_f32 v[26:27], v[26:27], v[28:29]
	s_nop 0
	v_pk_add_f32 v[24:25], v[24:25], v[26:27]
	v_mov_b32_e32 v27, v100
	v_mov_b32_e32 v26, v24
	v_mov_b32_e32 v100, v25
	v_pk_add_f32 v[24:25], v[26:27], v[100:101]
	ds_bpermute_b32 v27, v129, v25
	ds_bpermute_b32 v26, v129, v24
	s_waitcnt lgkmcnt(0)
	v_pk_add_f32 v[24:25], v[24:25], v[26:27]
	ds_bpermute_b32 v27, v2, v25
	ds_bpermute_b32 v26, v2, v24
	s_waitcnt lgkmcnt(0)
	v_pk_add_f32 v[24:25], v[24:25], v[26:27]
	s_nop 0
	v_pk_fma_f32 v[24:25], v[24:25], s[84:85], v[158:159] op_sel_hi:[1,0,0]
	s_nop 0
	v_mul_f32_e32 v2, 0x4b800000, v25
	v_cmp_gt_f32_e64 s[4:5], s75, v25
	v_cmp_gt_f32_e32 vcc, s75, v24
	s_nop 0
	v_cndmask_b32_e64 v2, v25, v2, s[4:5]
	v_rsq_f32_e32 v2, v2
	s_nop 0
	v_mul_f32_e32 v25, 0x45800000, v2
	v_cndmask_b32_e64 v2, v2, v25, s[4:5]
	v_pk_mul_f32 v[26:27], v[44:45], v[2:3] op_sel_hi:[1,0]
	v_pk_mul_f32 v[28:29], v[46:47], v[2:3] op_sel_hi:[1,0]
	s_waitcnt vmcnt(3)
	v_pk_mul_f32 v[26:27], v[16:17], v[26:27]
	v_pk_mul_f32 v[28:29], v[18:19], v[28:29]
	v_pk_mul_f32 v[26:27], v[78:79], v[26:27]
	v_pk_mul_f32 v[28:29], v[102:103], v[28:29]
	v_cvt_pk_bf16_f32 v26, v26, v27
	v_cvt_pk_bf16_f32 v27, v28, v29
	global_store_dwordx2 v[76:77], v[26:27], off offset:512 sc0 sc1
	v_pk_mul_f32 v[26:27], v[56:57], v[2:3] op_sel_hi:[1,0]
	v_pk_mul_f32 v[28:29], v[58:59], v[2:3] op_sel_hi:[1,0]
	s_waitcnt vmcnt(3)
	v_pk_mul_f32 v[26:27], v[12:13], v[26:27]
	v_pk_mul_f32 v[28:29], v[14:15], v[28:29]
	v_pk_mul_f32 v[26:27], v[104:105], v[26:27]
	v_pk_mul_f32 v[28:29], v[138:139], v[28:29]
	v_cvt_pk_bf16_f32 v26, v26, v27
	v_cvt_pk_bf16_f32 v27, v28, v29
	global_store_dwordx2 v[76:77], v[26:27], off offset:544 sc0 sc1
	v_pk_mul_f32 v[26:27], v[68:69], v[2:3] op_sel_hi:[1,0]
	v_pk_mul_f32 v[28:29], v[70:71], v[2:3] op_sel_hi:[1,0]
	s_waitcnt vmcnt(3)
	v_pk_mul_f32 v[26:27], v[8:9], v[26:27]
	v_pk_mul_f32 v[28:29], v[10:11], v[28:29]
	v_pk_mul_f32 v[26:27], v[142:143], v[26:27]
	v_pk_mul_f32 v[28:29], v[140:141], v[28:29]
	v_cvt_pk_bf16_f32 v26, v26, v27
	v_cvt_pk_bf16_f32 v27, v28, v29
	global_store_dwordx2 v[76:77], v[26:27], off offset:576 sc0 sc1
	v_pk_mul_f32 v[26:27], v[72:73], v[2:3] op_sel_hi:[1,0]
	v_pk_mul_f32 v[28:29], v[74:75], v[2:3] op_sel_hi:[1,0]
	s_waitcnt vmcnt(3)
	v_pk_mul_f32 v[26:27], v[4:5], v[26:27]
	v_pk_mul_f32 v[28:29], v[6:7], v[28:29]
	v_pk_mul_f32 v[26:27], v[144:145], v[26:27]
	v_pk_mul_f32 v[28:29], v[136:137], v[28:29]
	v_cvt_pk_bf16_f32 v26, v26, v27
	v_cvt_pk_bf16_f32 v27, v28, v29
	global_store_dwordx2 v[76:77], v[26:27], off offset:608 sc0 sc1
	v_lshlrev_b32_e32 v26, 16, v86
	v_and_b32_e32 v27, 0xffff0000, v86
	v_mul_f32_e32 v28, 0xbfb8aa3b, v26
	v_mul_f32_e32 v29, 0xbfb8aa3b, v27
	v_mul_f32_e32 v2, 0x4b800000, v24
	v_exp_f32_e32 v28, v28
	v_exp_f32_e32 v29, v29
	v_cndmask_b32_e32 v2, v24, v2, vcc
	v_rsq_f32_e32 v2, v2
	v_add_f32_e32 v28, 1.0, v28
	v_add_f32_e32 v29, 1.0, v29
	v_rcp_f32_e32 v28, v28
	v_rcp_f32_e32 v29, v29
	v_mul_f32_e32 v24, 0x45800000, v2
	v_cndmask_b32_e32 v2, v2, v24, vcc
	v_pk_mul_f32 v[30:31], v[60:61], v[2:3] op_sel_hi:[1,0]
	v_pk_mul_f32 v[26:27], v[28:29], v[26:27]
	v_pk_mul_f32 v[16:17], v[16:17], v[30:31]
	v_pk_mul_f32 v[30:31], v[62:63], v[2:3] op_sel_hi:[1,0]
	v_pk_mul_f32 v[16:17], v[26:27], v[16:17]
	v_lshlrev_b32_e32 v26, 16, v87
	v_cvt_pk_bf16_f32 v16, v16, v17
	v_mul_f32_e32 v17, 0xbfb8aa3b, v26
	v_exp_f32_e32 v17, v17
	v_and_b32_e32 v27, 0xffff0000, v87
	v_pk_mul_f32 v[18:19], v[18:19], v[30:31]
	v_lshlrev_b64 v[24:25], 11, v[90:91]
	v_add_f32_e32 v17, 1.0, v17
	v_rcp_f32_e32 v28, v17
	v_mul_f32_e32 v17, 0xbfb8aa3b, v27
	v_exp_f32_e32 v17, v17
	v_lshl_add_u64 v[24:25], v[94:95], 0, v[24:25]
	v_add_f32_e32 v17, 1.0, v17
	v_rcp_f32_e32 v29, v17
	s_nop 0
	v_pk_mul_f32 v[26:27], v[28:29], v[26:27]
	s_nop 0
	v_pk_mul_f32 v[18:19], v[26:27], v[18:19]
	v_pk_mul_f32 v[26:27], v[48:49], v[2:3] op_sel_hi:[1,0]
	v_cvt_pk_bf16_f32 v17, v18, v19
	global_store_dwordx2 v[24:25], v[16:17], off offset:512 sc0 sc1
	v_lshlrev_b32_e32 v16, 16, v84
	v_and_b32_e32 v17, 0xffff0000, v84
	v_mul_f32_e32 v18, 0xbfb8aa3b, v16
	v_mul_f32_e32 v19, 0xbfb8aa3b, v17
	v_exp_f32_e32 v18, v18
	v_exp_f32_e32 v19, v19
	v_pk_mul_f32 v[12:13], v[12:13], v[26:27]
	v_pk_mul_f32 v[26:27], v[50:51], v[2:3] op_sel_hi:[1,0]
	v_add_f32_e32 v18, 1.0, v18
	v_add_f32_e32 v19, 1.0, v19
	v_rcp_f32_e32 v18, v18
	v_rcp_f32_e32 v19, v19
	v_pk_mul_f32 v[14:15], v[14:15], v[26:27]
	v_pk_mul_f32 v[16:17], v[18:19], v[16:17]
	s_nop 0
	v_pk_mul_f32 v[12:13], v[16:17], v[12:13]
	v_lshlrev_b32_e32 v16, 16, v85
	v_cvt_pk_bf16_f32 v12, v12, v13
	v_mul_f32_e32 v13, 0xbfb8aa3b, v16
	v_exp_f32_e32 v13, v13
	v_and_b32_e32 v17, 0xffff0000, v85
	v_add_f32_e32 v13, 1.0, v13
	v_rcp_f32_e32 v18, v13
	v_mul_f32_e32 v13, 0xbfb8aa3b, v17
	v_exp_f32_e32 v13, v13
	s_nop 0
	v_add_f32_e32 v13, 1.0, v13
	v_rcp_f32_e32 v19, v13
	s_nop 0
	v_pk_mul_f32 v[16:17], v[18:19], v[16:17]
	s_nop 0
	v_pk_mul_f32 v[14:15], v[16:17], v[14:15]
	v_pk_mul_f32 v[16:17], v[36:37], v[2:3] op_sel_hi:[1,0]
	v_cvt_pk_bf16_f32 v13, v14, v15
	global_store_dwordx2 v[24:25], v[12:13], off offset:544 sc0 sc1
	v_lshlrev_b32_e32 v12, 16, v82
	v_and_b32_e32 v13, 0xffff0000, v82
	v_mul_f32_e32 v14, 0xbfb8aa3b, v12
	v_mul_f32_e32 v15, 0xbfb8aa3b, v13
	v_exp_f32_e32 v14, v14
	v_exp_f32_e32 v15, v15
	v_pk_mul_f32 v[8:9], v[8:9], v[16:17]
	v_pk_mul_f32 v[16:17], v[38:39], v[2:3] op_sel_hi:[1,0]
	v_add_f32_e32 v14, 1.0, v14
	v_add_f32_e32 v15, 1.0, v15
	v_rcp_f32_e32 v14, v14
	v_rcp_f32_e32 v15, v15
	v_pk_mul_f32 v[10:11], v[10:11], v[16:17]
	v_pk_mul_f32 v[12:13], v[14:15], v[12:13]
	s_nop 0
	v_pk_mul_f32 v[8:9], v[12:13], v[8:9]
	v_lshlrev_b32_e32 v12, 16, v83
	v_cvt_pk_bf16_f32 v8, v8, v9
	v_mul_f32_e32 v9, 0xbfb8aa3b, v12
	v_exp_f32_e32 v9, v9
	v_and_b32_e32 v13, 0xffff0000, v83
	v_add_f32_e32 v9, 1.0, v9
	v_rcp_f32_e32 v14, v9
	v_mul_f32_e32 v9, 0xbfb8aa3b, v13
	v_exp_f32_e32 v9, v9
	s_nop 0
	v_add_f32_e32 v9, 1.0, v9
	v_rcp_f32_e32 v15, v9
	s_nop 0
	v_pk_mul_f32 v[12:13], v[14:15], v[12:13]
	s_nop 0
	v_pk_mul_f32 v[10:11], v[12:13], v[10:11]
	v_pk_mul_f32 v[12:13], v[20:21], v[2:3] op_sel_hi:[1,0]
	v_cvt_pk_bf16_f32 v9, v10, v11
	global_store_dwordx2 v[24:25], v[8:9], off offset:576 sc0 sc1
	v_lshlrev_b32_e32 v8, 16, v80
	v_and_b32_e32 v9, 0xffff0000, v80
	v_mul_f32_e32 v10, 0xbfb8aa3b, v8
	v_mul_f32_e32 v11, 0xbfb8aa3b, v9
	v_exp_f32_e32 v10, v10
	v_exp_f32_e32 v11, v11
	v_pk_mul_f32 v[4:5], v[4:5], v[12:13]
	v_pk_mul_f32 v[12:13], v[22:23], v[2:3] op_sel_hi:[1,0]
	v_add_f32_e32 v10, 1.0, v10
	v_add_f32_e32 v11, 1.0, v11
	v_rcp_f32_e32 v10, v10
	v_rcp_f32_e32 v11, v11
	v_pk_mul_f32 v[6:7], v[6:7], v[12:13]
	v_pk_mul_f32 v[8:9], v[10:11], v[8:9]
	s_nop 0
	v_pk_mul_f32 v[4:5], v[8:9], v[4:5]
	v_lshlrev_b32_e32 v8, 16, v81
	v_and_b32_e32 v9, 0xffff0000, v81
	v_cvt_pk_bf16_f32 v4, v4, v5
	v_mul_f32_e32 v5, 0xbfb8aa3b, v8
	v_mul_f32_e32 v2, 0xbfb8aa3b, v9
	v_exp_f32_e32 v5, v5
	v_exp_f32_e32 v2, v2
	v_add_f32_e32 v5, 1.0, v5
	v_add_f32_e32 v2, 1.0, v2
	v_rcp_f32_e32 v10, v5
	v_rcp_f32_e32 v11, v2
	s_nop 0
	v_pk_mul_f32 v[8:9], v[10:11], v[8:9]
	s_nop 0
	v_pk_mul_f32 v[6:7], v[8:9], v[6:7]
	s_nop 0
	v_cvt_pk_bf16_f32 v5, v6, v7
	global_store_dwordx2 v[24:25], v[4:5], off offset:608 sc0 sc1
	s_branch .LBB0_952
